# v70 + software-pipelined EpiResid epilogues (8-deep residual loads, reordered column groups) for FFN-out non-final and mixer-out tiles
# baseline (speedup 1.0000x reference)
.LBB0_279:
	v_readlane_b32 s28, v250, 53
	s_nop 3
	s_cmp_eq_u32 s28, 3
	s_cbranch_scc1 .Lepi_A_final
	v_lshl_add_u32 v136, s58, 8, v158
	v_lshl_or_b32 v137, s2, 8, v159
	v_lshlrev_b32_e32 v136, 3, v136
	v_lshlrev_b32_e32 v137, 2, v137
	s_ashr_i32 s59, s58, 31
	s_lshl_b64 s[28:29], s[58:59], 20
	s_add_u32 s60, s73, s28
	s_addc_u32 s61, s72, s29
	v_readlane_b32 s4, v252, 0
	v_readlane_b32 s5, v252, 1
	v_readlane_b32 s6, v252, 2
	v_readlane_b32 s7, v252, 3
	v_readlane_b32 s8, v252, 4
	v_readlane_b32 s9, v252, 5
	v_readlane_b32 s10, v252, 6
	v_readlane_b32 s11, v252, 7
	v_readlane_b32 s12, v252, 8
	v_readlane_b32 s13, v252, 9
	v_readlane_b32 s14, v252, 10
	v_readlane_b32 s15, v252, 11
	v_readlane_b32 s16, v252, 12
	v_readlane_b32 s17, v252, 13
	s_mov_b64 s[4:5], s[8:9]
	v_readlane_b32 s18, v252, 14
	v_readlane_b32 s19, v252, 15
	s_mov_b64 s[6:7], s[10:11]
	s_mov_b64 s[8:9], s[12:13]
	s_mov_b64 s[12:13], s[16:17]
	s_add_u32 s58, s12, s28
	s_addc_u32 s59, s13, s29
	s_mov_b64 s[14:15], s[18:19]
	s_and_b64 vcc, exec, s[80:81]
	s_cbranch_vccz .Lepi_A_nostats
	s_mov_b64 s[40:41], 0
	global_load_dwordx2 v[240:241], v136, s[92:93]
	global_load_dwordx2 v[242:243], v136, s[92:93] offset:128
	global_load_dwordx2 v[244:245], v136, s[92:93] offset:256
	global_load_dwordx2 v[246:247], v136, s[92:93] offset:384
	global_load_dwordx2 v[248:249], v136, s[92:93] offset:1024
	global_load_dwordx2 v[220:221], v136, s[92:93] offset:1152
	global_load_dwordx2 v[108:109], v136, s[92:93] offset:1280
	global_load_dwordx2 v[110:111], v136, s[92:93] offset:1408
	global_load_dwordx4 v[212:215], v137, s[48:49]
	global_load_dwordx4 v[216:219], v137, s[84:85]
	v_lshl_add_u32 v112, v160, 2, v137
	v_lshl_add_u32 v113, v164, 2, v137
	v_lshl_add_u32 v130, v166, 2, v137
	v_lshl_add_u32 v131, v168, 2, v137
	v_lshl_add_u32 v132, v162, 2, v137
	v_lshl_add_u32 v133, v170, 2, v137
	v_lshl_add_u32 v134, v172, 2, v137
	v_lshl_add_u32 v135, v174, 2, v137
	global_load_dwordx4 v[180:183], v112, s[60:61]
	global_load_dwordx4 v[184:187], v113, s[60:61]
	global_load_dwordx4 v[188:191], v130, s[60:61]
	global_load_dwordx4 v[192:195], v131, s[60:61]
	global_load_dwordx4 v[196:199], v132, s[60:61]
	global_load_dwordx4 v[200:203], v133, s[60:61]
	global_load_dwordx4 v[204:207], v134, s[60:61]
	global_load_dwordx4 v[208:211], v135, s[60:61]
	global_load_dwordx4 v[232:235], v137, s[48:49] offset:512
	global_load_dwordx4 v[236:239], v137, s[84:85] offset:512
	s_waitcnt vmcnt(9)
	v_pk_add_f32 v[180:181], v[180:181], v[240:241] op_sel_hi:[1,0] neg_lo:[0,1] neg_hi:[0,1]
	v_pk_add_f32 v[182:183], v[182:183], v[240:241] op_sel_hi:[1,0] neg_lo:[0,1] neg_hi:[0,1]
	v_pk_mul_f32 v[180:181], v[180:181], v[240:241] op_sel:[0,1] op_sel_hi:[1,1]
	v_pk_mul_f32 v[182:183], v[182:183], v[240:241] op_sel:[0,1] op_sel_hi:[1,1]
	v_pk_fma_f32 v[180:181], v[212:213], v[180:181], v[216:217]
	v_pk_fma_f32 v[182:183], v[214:215], v[182:183], v[218:219]
	v_pk_mul_f32 v[180:181], v[180:181], s[82:83] op_sel_hi:[1,0]
	v_pk_mul_f32 v[182:183], v[182:183], s[82:83] op_sel_hi:[1,0]
	v_pk_fma_f32 v[138:139], v[138:139], 0.5, v[180:181] op_sel_hi:[1,0,1]
	v_pk_fma_f32 v[140:141], v[140:141], 0.5, v[182:183] op_sel_hi:[1,0,1]
	s_nop 0
	global_store_dwordx4 v112, v[138:141], s[58:59] sc1
	global_load_dwordx4 v[180:183], v112, s[60:61] offset:512
	s_waitcnt vmcnt(10)
	v_pk_add_f32 v[184:185], v[184:185], v[242:243] op_sel_hi:[1,0] neg_lo:[0,1] neg_hi:[0,1]
	v_pk_add_f32 v[186:187], v[186:187], v[242:243] op_sel_hi:[1,0] neg_lo:[0,1] neg_hi:[0,1]
	v_pk_mul_f32 v[184:185], v[184:185], v[242:243] op_sel:[0,1] op_sel_hi:[1,1]
	v_pk_mul_f32 v[186:187], v[186:187], v[242:243] op_sel:[0,1] op_sel_hi:[1,1]
	v_pk_fma_f32 v[184:185], v[212:213], v[184:185], v[216:217]
	v_pk_fma_f32 v[186:187], v[214:215], v[186:187], v[218:219]
	v_pk_mul_f32 v[184:185], v[184:185], s[82:83] op_sel_hi:[1,0]
	v_pk_mul_f32 v[186:187], v[186:187], s[82:83] op_sel_hi:[1,0]
	v_pk_fma_f32 v[126:127], v[126:127], 0.5, v[184:185] op_sel_hi:[1,0,1]
	v_pk_fma_f32 v[128:129], v[128:129], 0.5, v[186:187] op_sel_hi:[1,0,1]
	s_nop 0
	global_store_dwordx4 v113, v[126:129], s[58:59] sc1
	global_load_dwordx4 v[184:187], v113, s[60:61] offset:512
	s_waitcnt vmcnt(11)
	v_pk_add_f32 v[188:189], v[188:189], v[244:245] op_sel_hi:[1,0] neg_lo:[0,1] neg_hi:[0,1]
	v_pk_add_f32 v[190:191], v[190:191], v[244:245] op_sel_hi:[1,0] neg_lo:[0,1] neg_hi:[0,1]
	v_pk_mul_f32 v[188:189], v[188:189], v[244:245] op_sel:[0,1] op_sel_hi:[1,1]
	v_pk_mul_f32 v[190:191], v[190:191], v[244:245] op_sel:[0,1] op_sel_hi:[1,1]
	v_pk_fma_f32 v[188:189], v[212:213], v[188:189], v[216:217]
	v_pk_fma_f32 v[190:191], v[214:215], v[190:191], v[218:219]
	v_pk_mul_f32 v[188:189], v[188:189], s[82:83] op_sel_hi:[1,0]
	v_pk_mul_f32 v[190:191], v[190:191], s[82:83] op_sel_hi:[1,0]
	v_pk_fma_f32 v[122:123], v[122:123], 0.5, v[188:189] op_sel_hi:[1,0,1]
	v_pk_fma_f32 v[124:125], v[124:125], 0.5, v[190:191] op_sel_hi:[1,0,1]
	s_nop 0
	global_store_dwordx4 v130, v[122:125], s[58:59] sc1
	global_load_dwordx4 v[188:191], v130, s[60:61] offset:512
	s_waitcnt vmcnt(12)
	v_pk_add_f32 v[192:193], v[192:193], v[246:247] op_sel_hi:[1,0] neg_lo:[0,1] neg_hi:[0,1]
	v_pk_add_f32 v[194:195], v[194:195], v[246:247] op_sel_hi:[1,0] neg_lo:[0,1] neg_hi:[0,1]
	v_pk_mul_f32 v[192:193], v[192:193], v[246:247] op_sel:[0,1] op_sel_hi:[1,1]
	v_pk_mul_f32 v[194:195], v[194:195], v[246:247] op_sel:[0,1] op_sel_hi:[1,1]
	v_pk_fma_f32 v[192:193], v[212:213], v[192:193], v[216:217]
	v_pk_fma_f32 v[194:195], v[214:215], v[194:195], v[218:219]
	v_pk_mul_f32 v[192:193], v[192:193], s[82:83] op_sel_hi:[1,0]
	v_pk_mul_f32 v[194:195], v[194:195], s[82:83] op_sel_hi:[1,0]
	v_pk_fma_f32 v[118:119], v[118:119], 0.5, v[192:193] op_sel_hi:[1,0,1]
	v_pk_fma_f32 v[120:121], v[120:121], 0.5, v[194:195] op_sel_hi:[1,0,1]
	s_nop 0
	global_store_dwordx4 v131, v[118:121], s[58:59] sc1
	global_load_dwordx4 v[192:195], v131, s[60:61] offset:512
	s_waitcnt vmcnt(13)
	v_pk_add_f32 v[196:197], v[196:197], v[248:249] op_sel_hi:[1,0] neg_lo:[0,1] neg_hi:[0,1]
	v_pk_add_f32 v[198:199], v[198:199], v[248:249] op_sel_hi:[1,0] neg_lo:[0,1] neg_hi:[0,1]
	v_pk_mul_f32 v[196:197], v[196:197], v[248:249] op_sel:[0,1] op_sel_hi:[1,1]
	v_pk_mul_f32 v[198:199], v[198:199], v[248:249] op_sel:[0,1] op_sel_hi:[1,1]
	v_pk_fma_f32 v[196:197], v[212:213], v[196:197], v[216:217]
	v_pk_fma_f32 v[198:199], v[214:215], v[198:199], v[218:219]
	v_pk_mul_f32 v[196:197], v[196:197], s[82:83] op_sel_hi:[1,0]
	v_pk_mul_f32 v[198:199], v[198:199], s[82:83] op_sel_hi:[1,0]
	v_pk_fma_f32 v[114:115], v[114:115], 0.5, v[196:197] op_sel_hi:[1,0,1]
	v_pk_fma_f32 v[116:117], v[116:117], 0.5, v[198:199] op_sel_hi:[1,0,1]
	s_nop 0
	global_store_dwordx4 v132, v[114:117], s[58:59] sc1
	global_load_dwordx4 v[196:199], v132, s[60:61] offset:512
	s_waitcnt vmcnt(14)
	v_pk_add_f32 v[200:201], v[200:201], v[220:221] op_sel_hi:[1,0] neg_lo:[0,1] neg_hi:[0,1]
	v_pk_add_f32 v[202:203], v[202:203], v[220:221] op_sel_hi:[1,0] neg_lo:[0,1] neg_hi:[0,1]
	v_pk_mul_f32 v[200:201], v[200:201], v[220:221] op_sel:[0,1] op_sel_hi:[1,1]
	v_pk_mul_f32 v[202:203], v[202:203], v[220:221] op_sel:[0,1] op_sel_hi:[1,1]
	v_pk_fma_f32 v[200:201], v[212:213], v[200:201], v[216:217]
	v_pk_fma_f32 v[202:203], v[214:215], v[202:203], v[218:219]
	v_pk_mul_f32 v[200:201], v[200:201], s[82:83] op_sel_hi:[1,0]
	v_pk_mul_f32 v[202:203], v[202:203], s[82:83] op_sel_hi:[1,0]
	v_pk_fma_f32 v[104:105], v[104:105], 0.5, v[200:201] op_sel_hi:[1,0,1]
	v_pk_fma_f32 v[106:107], v[106:107], 0.5, v[202:203] op_sel_hi:[1,0,1]
	s_nop 0
	global_store_dwordx4 v133, v[104:107], s[58:59] sc1
	global_load_dwordx4 v[200:203], v133, s[60:61] offset:512
	s_waitcnt vmcnt(15)
	v_pk_add_f32 v[204:205], v[204:205], v[108:109] op_sel_hi:[1,0] neg_lo:[0,1] neg_hi:[0,1]
	v_pk_add_f32 v[206:207], v[206:207], v[108:109] op_sel_hi:[1,0] neg_lo:[0,1] neg_hi:[0,1]
	v_pk_mul_f32 v[204:205], v[204:205], v[108:109] op_sel:[0,1] op_sel_hi:[1,1]
	v_pk_mul_f32 v[206:207], v[206:207], v[108:109] op_sel:[0,1] op_sel_hi:[1,1]
	v_pk_fma_f32 v[204:205], v[212:213], v[204:205], v[216:217]
	v_pk_fma_f32 v[206:207], v[214:215], v[206:207], v[218:219]
	v_pk_mul_f32 v[204:205], v[204:205], s[82:83] op_sel_hi:[1,0]
	v_pk_mul_f32 v[206:207], v[206:207], s[82:83] op_sel_hi:[1,0]
	v_pk_fma_f32 v[100:101], v[100:101], 0.5, v[204:205] op_sel_hi:[1,0,1]
	v_pk_fma_f32 v[102:103], v[102:103], 0.5, v[206:207] op_sel_hi:[1,0,1]
	s_nop 0
	global_store_dwordx4 v134, v[100:103], s[58:59] sc1
	global_load_dwordx4 v[204:207], v134, s[60:61] offset:512
	s_waitcnt vmcnt(16)
	v_pk_add_f32 v[208:209], v[208:209], v[110:111] op_sel_hi:[1,0] neg_lo:[0,1] neg_hi:[0,1]
	v_pk_add_f32 v[210:211], v[210:211], v[110:111] op_sel_hi:[1,0] neg_lo:[0,1] neg_hi:[0,1]
	v_pk_mul_f32 v[208:209], v[208:209], v[110:111] op_sel:[0,1] op_sel_hi:[1,1]
	v_pk_mul_f32 v[210:211], v[210:211], v[110:111] op_sel:[0,1] op_sel_hi:[1,1]
	v_pk_fma_f32 v[208:209], v[212:213], v[208:209], v[216:217]
	v_pk_fma_f32 v[210:211], v[214:215], v[210:211], v[218:219]
	v_pk_mul_f32 v[208:209], v[208:209], s[82:83] op_sel_hi:[1,0]
	v_pk_mul_f32 v[210:211], v[210:211], s[82:83] op_sel_hi:[1,0]
	v_pk_fma_f32 v[96:97], v[96:97], 0.5, v[208:209] op_sel_hi:[1,0,1]
	v_pk_fma_f32 v[98:99], v[98:99], 0.5, v[210:211] op_sel_hi:[1,0,1]
	s_nop 0
	global_store_dwordx4 v135, v[96:99], s[58:59] sc1
	global_load_dwordx4 v[208:211], v135, s[60:61] offset:512
	global_load_dwordx4 v[212:215], v137, s[48:49] offset:64
	global_load_dwordx4 v[216:219], v137, s[84:85] offset:64
	s_waitcnt vmcnt(16)
	v_pk_add_f32 v[180:181], v[180:181], v[240:241] op_sel_hi:[1,0] neg_lo:[0,1] neg_hi:[0,1]
	v_pk_add_f32 v[182:183], v[182:183], v[240:241] op_sel_hi:[1,0] neg_lo:[0,1] neg_hi:[0,1]
	v_pk_mul_f32 v[180:181], v[180:181], v[240:241] op_sel:[0,1] op_sel_hi:[1,1]
	v_pk_mul_f32 v[182:183], v[182:183], v[240:241] op_sel:[0,1] op_sel_hi:[1,1]
	v_pk_fma_f32 v[180:181], v[232:233], v[180:181], v[236:237]
	v_pk_fma_f32 v[182:183], v[234:235], v[182:183], v[238:239]
	v_pk_mul_f32 v[180:181], v[180:181], s[82:83] op_sel_hi:[1,0]
	v_pk_mul_f32 v[182:183], v[182:183], s[82:83] op_sel_hi:[1,0]
	v_pk_fma_f32 v[60:61], v[60:61], 0.5, v[180:181] op_sel_hi:[1,0,1]
	v_pk_fma_f32 v[62:63], v[62:63], 0.5, v[182:183] op_sel_hi:[1,0,1]
	s_nop 0
	global_store_dwordx4 v112, v[60:63], s[58:59] offset:512 sc1
	global_load_dwordx4 v[180:183], v112, s[60:61] offset:64
	s_waitcnt vmcnt(16)
	v_pk_add_f32 v[184:185], v[184:185], v[242:243] op_sel_hi:[1,0] neg_lo:[0,1] neg_hi:[0,1]
	v_pk_add_f32 v[186:187], v[186:187], v[242:243] op_sel_hi:[1,0] neg_lo:[0,1] neg_hi:[0,1]
	v_pk_mul_f32 v[184:185], v[184:185], v[242:243] op_sel:[0,1] op_sel_hi:[1,1]
	v_pk_mul_f32 v[186:187], v[186:187], v[242:243] op_sel:[0,1] op_sel_hi:[1,1]
	v_pk_fma_f32 v[184:185], v[232:233], v[184:185], v[236:237]
	v_pk_fma_f32 v[186:187], v[234:235], v[186:187], v[238:239]
	v_pk_mul_f32 v[184:185], v[184:185], s[82:83] op_sel_hi:[1,0]
	v_pk_mul_f32 v[186:187], v[186:187], s[82:83] op_sel_hi:[1,0]
	v_pk_fma_f32 v[56:57], v[56:57], 0.5, v[184:185] op_sel_hi:[1,0,1]
	v_pk_fma_f32 v[58:59], v[58:59], 0.5, v[186:187] op_sel_hi:[1,0,1]
	s_nop 0
	global_store_dwordx4 v113, v[56:59], s[58:59] offset:512 sc1
	global_load_dwordx4 v[184:187], v113, s[60:61] offset:64
	s_waitcnt vmcnt(16)
	v_pk_add_f32 v[188:189], v[188:189], v[244:245] op_sel_hi:[1,0] neg_lo:[0,1] neg_hi:[0,1]
	v_pk_add_f32 v[190:191], v[190:191], v[244:245] op_sel_hi:[1,0] neg_lo:[0,1] neg_hi:[0,1]
	v_pk_mul_f32 v[188:189], v[188:189], v[244:245] op_sel:[0,1] op_sel_hi:[1,1]
	v_pk_mul_f32 v[190:191], v[190:191], v[244:245] op_sel:[0,1] op_sel_hi:[1,1]
	v_pk_fma_f32 v[188:189], v[232:233], v[188:189], v[236:237]
	v_pk_fma_f32 v[190:191], v[234:235], v[190:191], v[238:239]
	v_pk_mul_f32 v[188:189], v[188:189], s[82:83] op_sel_hi:[1,0]
	v_pk_mul_f32 v[190:191], v[190:191], s[82:83] op_sel_hi:[1,0]
	v_pk_fma_f32 v[52:53], v[52:53], 0.5, v[188:189] op_sel_hi:[1,0,1]
	v_pk_fma_f32 v[54:55], v[54:55], 0.5, v[190:191] op_sel_hi:[1,0,1]
	s_nop 0
	global_store_dwordx4 v130, v[52:55], s[58:59] offset:512 sc1
	global_load_dwordx4 v[188:191], v130, s[60:61] offset:64
	s_waitcnt vmcnt(16)
	v_pk_add_f32 v[192:193], v[192:193], v[246:247] op_sel_hi:[1,0] neg_lo:[0,1] neg_hi:[0,1]
	v_pk_add_f32 v[194:195], v[194:195], v[246:247] op_sel_hi:[1,0] neg_lo:[0,1] neg_hi:[0,1]
	v_pk_mul_f32 v[192:193], v[192:193], v[246:247] op_sel:[0,1] op_sel_hi:[1,1]
	v_pk_mul_f32 v[194:195], v[194:195], v[246:247] op_sel:[0,1] op_sel_hi:[1,1]
	v_pk_fma_f32 v[192:193], v[232:233], v[192:193], v[236:237]
	v_pk_fma_f32 v[194:195], v[234:235], v[194:195], v[238:239]
	v_pk_mul_f32 v[192:193], v[192:193], s[82:83] op_sel_hi:[1,0]
	v_pk_mul_f32 v[194:195], v[194:195], s[82:83] op_sel_hi:[1,0]
	v_pk_fma_f32 v[48:49], v[48:49], 0.5, v[192:193] op_sel_hi:[1,0,1]
	v_pk_fma_f32 v[50:51], v[50:51], 0.5, v[194:195] op_sel_hi:[1,0,1]
	s_nop 0
	global_store_dwordx4 v131, v[48:51], s[58:59] offset:512 sc1
	global_load_dwordx4 v[192:195], v131, s[60:61] offset:64
	s_waitcnt vmcnt(16)
	v_pk_add_f32 v[196:197], v[196:197], v[248:249] op_sel_hi:[1,0] neg_lo:[0,1] neg_hi:[0,1]
	v_pk_add_f32 v[198:199], v[198:199], v[248:249] op_sel_hi:[1,0] neg_lo:[0,1] neg_hi:[0,1]
	v_pk_mul_f32 v[196:197], v[196:197], v[248:249] op_sel:[0,1] op_sel_hi:[1,1]
	v_pk_mul_f32 v[198:199], v[198:199], v[248:249] op_sel:[0,1] op_sel_hi:[1,1]
	v_pk_fma_f32 v[196:197], v[232:233], v[196:197], v[236:237]
	v_pk_fma_f32 v[198:199], v[234:235], v[198:199], v[238:239]
	v_pk_mul_f32 v[196:197], v[196:197], s[82:83] op_sel_hi:[1,0]
	v_pk_mul_f32 v[198:199], v[198:199], s[82:83] op_sel_hi:[1,0]
	v_pk_fma_f32 v[44:45], v[44:45], 0.5, v[196:197] op_sel_hi:[1,0,1]
	v_pk_fma_f32 v[46:47], v[46:47], 0.5, v[198:199] op_sel_hi:[1,0,1]
	s_nop 0
	global_store_dwordx4 v132, v[44:47], s[58:59] offset:512 sc1
	global_load_dwordx4 v[196:199], v132, s[60:61] offset:64
	s_waitcnt vmcnt(16)
	v_pk_add_f32 v[200:201], v[200:201], v[220:221] op_sel_hi:[1,0] neg_lo:[0,1] neg_hi:[0,1]
	v_pk_add_f32 v[202:203], v[202:203], v[220:221] op_sel_hi:[1,0] neg_lo:[0,1] neg_hi:[0,1]
	v_pk_mul_f32 v[200:201], v[200:201], v[220:221] op_sel:[0,1] op_sel_hi:[1,1]
	v_pk_mul_f32 v[202:203], v[202:203], v[220:221] op_sel:[0,1] op_sel_hi:[1,1]
	v_pk_fma_f32 v[200:201], v[232:233], v[200:201], v[236:237]
	v_pk_fma_f32 v[202:203], v[234:235], v[202:203], v[238:239]
	v_pk_mul_f32 v[200:201], v[200:201], s[82:83] op_sel_hi:[1,0]
	v_pk_mul_f32 v[202:203], v[202:203], s[82:83] op_sel_hi:[1,0]
	v_pk_fma_f32 v[40:41], v[40:41], 0.5, v[200:201] op_sel_hi:[1,0,1]
	v_pk_fma_f32 v[42:43], v[42:43], 0.5, v[202:203] op_sel_hi:[1,0,1]
	s_nop 0
	global_store_dwordx4 v133, v[40:43], s[58:59] offset:512 sc1
	global_load_dwordx4 v[200:203], v133, s[60:61] offset:64
	s_waitcnt vmcnt(16)
	v_pk_add_f32 v[204:205], v[204:205], v[108:109] op_sel_hi:[1,0] neg_lo:[0,1] neg_hi:[0,1]
	v_pk_add_f32 v[206:207], v[206:207], v[108:109] op_sel_hi:[1,0] neg_lo:[0,1] neg_hi:[0,1]
	v_pk_mul_f32 v[204:205], v[204:205], v[108:109] op_sel:[0,1] op_sel_hi:[1,1]
	v_pk_mul_f32 v[206:207], v[206:207], v[108:109] op_sel:[0,1] op_sel_hi:[1,1]
	v_pk_fma_f32 v[204:205], v[232:233], v[204:205], v[236:237]
	v_pk_fma_f32 v[206:207], v[234:235], v[206:207], v[238:239]
	v_pk_mul_f32 v[204:205], v[204:205], s[82:83] op_sel_hi:[1,0]
	v_pk_mul_f32 v[206:207], v[206:207], s[82:83] op_sel_hi:[1,0]
	v_pk_fma_f32 v[36:37], v[36:37], 0.5, v[204:205] op_sel_hi:[1,0,1]
	v_pk_fma_f32 v[38:39], v[38:39], 0.5, v[206:207] op_sel_hi:[1,0,1]
	s_nop 0
	global_store_dwordx4 v134, v[36:39], s[58:59] offset:512 sc1
	global_load_dwordx4 v[204:207], v134, s[60:61] offset:64
	s_waitcnt vmcnt(16)
	v_pk_add_f32 v[208:209], v[208:209], v[110:111] op_sel_hi:[1,0] neg_lo:[0,1] neg_hi:[0,1]
	v_pk_add_f32 v[210:211], v[210:211], v[110:111] op_sel_hi:[1,0] neg_lo:[0,1] neg_hi:[0,1]
	v_pk_mul_f32 v[208:209], v[208:209], v[110:111] op_sel:[0,1] op_sel_hi:[1,1]
	v_pk_mul_f32 v[210:211], v[210:211], v[110:111] op_sel:[0,1] op_sel_hi:[1,1]
	v_pk_fma_f32 v[208:209], v[232:233], v[208:209], v[236:237]
	v_pk_fma_f32 v[210:211], v[234:235], v[210:211], v[238:239]
	v_pk_mul_f32 v[208:209], v[208:209], s[82:83] op_sel_hi:[1,0]
	v_pk_mul_f32 v[210:211], v[210:211], s[82:83] op_sel_hi:[1,0]
	v_pk_fma_f32 v[32:33], v[32:33], 0.5, v[208:209] op_sel_hi:[1,0,1]
	v_pk_fma_f32 v[34:35], v[34:35], 0.5, v[210:211] op_sel_hi:[1,0,1]
	s_nop 0
	global_store_dwordx4 v135, v[32:35], s[58:59] offset:512 sc1
	global_load_dwordx4 v[208:211], v135, s[60:61] offset:64
	global_load_dwordx4 v[232:235], v137, s[48:49] offset:576
	global_load_dwordx4 v[236:239], v137, s[84:85] offset:576
	s_waitcnt vmcnt(16)
	v_pk_add_f32 v[180:181], v[180:181], v[240:241] op_sel_hi:[1,0] neg_lo:[0,1] neg_hi:[0,1]
	v_pk_add_f32 v[182:183], v[182:183], v[240:241] op_sel_hi:[1,0] neg_lo:[0,1] neg_hi:[0,1]
	v_pk_mul_f32 v[180:181], v[180:181], v[240:241] op_sel:[0,1] op_sel_hi:[1,1]
	v_pk_mul_f32 v[182:183], v[182:183], v[240:241] op_sel:[0,1] op_sel_hi:[1,1]
	v_pk_fma_f32 v[180:181], v[212:213], v[180:181], v[216:217]
	v_pk_fma_f32 v[182:183], v[214:215], v[182:183], v[218:219]
	v_pk_mul_f32 v[180:181], v[180:181], s[82:83] op_sel_hi:[1,0]
	v_pk_mul_f32 v[182:183], v[182:183], s[82:83] op_sel_hi:[1,0]
	v_pk_fma_f32 v[92:93], v[92:93], 0.5, v[180:181] op_sel_hi:[1,0,1]
	v_pk_fma_f32 v[94:95], v[94:95], 0.5, v[182:183] op_sel_hi:[1,0,1]
	s_nop 0
	global_store_dwordx4 v112, v[92:95], s[58:59] offset:64 sc1
	global_load_dwordx4 v[180:183], v112, s[60:61] offset:576
	s_waitcnt vmcnt(16)
	v_pk_add_f32 v[184:185], v[184:185], v[242:243] op_sel_hi:[1,0] neg_lo:[0,1] neg_hi:[0,1]
	v_pk_add_f32 v[186:187], v[186:187], v[242:243] op_sel_hi:[1,0] neg_lo:[0,1] neg_hi:[0,1]
	v_pk_mul_f32 v[184:185], v[184:185], v[242:243] op_sel:[0,1] op_sel_hi:[1,1]
	v_pk_mul_f32 v[186:187], v[186:187], v[242:243] op_sel:[0,1] op_sel_hi:[1,1]
	v_pk_fma_f32 v[184:185], v[212:213], v[184:185], v[216:217]
	v_pk_fma_f32 v[186:187], v[214:215], v[186:187], v[218:219]
	v_pk_mul_f32 v[184:185], v[184:185], s[82:83] op_sel_hi:[1,0]
	v_pk_mul_f32 v[186:187], v[186:187], s[82:83] op_sel_hi:[1,0]
	v_pk_fma_f32 v[88:89], v[88:89], 0.5, v[184:185] op_sel_hi:[1,0,1]
	v_pk_fma_f32 v[90:91], v[90:91], 0.5, v[186:187] op_sel_hi:[1,0,1]
	s_nop 0
	global_store_dwordx4 v113, v[88:91], s[58:59] offset:64 sc1
	global_load_dwordx4 v[184:187], v113, s[60:61] offset:576
	s_waitcnt vmcnt(16)
	v_pk_add_f32 v[188:189], v[188:189], v[244:245] op_sel_hi:[1,0] neg_lo:[0,1] neg_hi:[0,1]
	v_pk_add_f32 v[190:191], v[190:191], v[244:245] op_sel_hi:[1,0] neg_lo:[0,1] neg_hi:[0,1]
	v_pk_mul_f32 v[188:189], v[188:189], v[244:245] op_sel:[0,1] op_sel_hi:[1,1]
	v_pk_mul_f32 v[190:191], v[190:191], v[244:245] op_sel:[0,1] op_sel_hi:[1,1]
	v_pk_fma_f32 v[188:189], v[212:213], v[188:189], v[216:217]
	v_pk_fma_f32 v[190:191], v[214:215], v[190:191], v[218:219]
	v_pk_mul_f32 v[188:189], v[188:189], s[82:83] op_sel_hi:[1,0]
	v_pk_mul_f32 v[190:191], v[190:191], s[82:83] op_sel_hi:[1,0]
	v_pk_fma_f32 v[84:85], v[84:85], 0.5, v[188:189] op_sel_hi:[1,0,1]
	v_pk_fma_f32 v[86:87], v[86:87], 0.5, v[190:191] op_sel_hi:[1,0,1]
	s_nop 0
	global_store_dwordx4 v130, v[84:87], s[58:59] offset:64 sc1
	global_load_dwordx4 v[188:191], v130, s[60:61] offset:576
	s_waitcnt vmcnt(16)
	v_pk_add_f32 v[192:193], v[192:193], v[246:247] op_sel_hi:[1,0] neg_lo:[0,1] neg_hi:[0,1]
	v_pk_add_f32 v[194:195], v[194:195], v[246:247] op_sel_hi:[1,0] neg_lo:[0,1] neg_hi:[0,1]
	v_pk_mul_f32 v[192:193], v[192:193], v[246:247] op_sel:[0,1] op_sel_hi:[1,1]
	v_pk_mul_f32 v[194:195], v[194:195], v[246:247] op_sel:[0,1] op_sel_hi:[1,1]
	v_pk_fma_f32 v[192:193], v[212:213], v[192:193], v[216:217]
	v_pk_fma_f32 v[194:195], v[214:215], v[194:195], v[218:219]
	v_pk_mul_f32 v[192:193], v[192:193], s[82:83] op_sel_hi:[1,0]
	v_pk_mul_f32 v[194:195], v[194:195], s[82:83] op_sel_hi:[1,0]
	v_pk_fma_f32 v[80:81], v[80:81], 0.5, v[192:193] op_sel_hi:[1,0,1]
	v_pk_fma_f32 v[82:83], v[82:83], 0.5, v[194:195] op_sel_hi:[1,0,1]
	s_nop 0
	global_store_dwordx4 v131, v[80:83], s[58:59] offset:64 sc1
	global_load_dwordx4 v[192:195], v131, s[60:61] offset:576
	s_waitcnt vmcnt(16)
	v_pk_add_f32 v[196:197], v[196:197], v[248:249] op_sel_hi:[1,0] neg_lo:[0,1] neg_hi:[0,1]
	v_pk_add_f32 v[198:199], v[198:199], v[248:249] op_sel_hi:[1,0] neg_lo:[0,1] neg_hi:[0,1]
	v_pk_mul_f32 v[196:197], v[196:197], v[248:249] op_sel:[0,1] op_sel_hi:[1,1]
	v_pk_mul_f32 v[198:199], v[198:199], v[248:249] op_sel:[0,1] op_sel_hi:[1,1]
	v_pk_fma_f32 v[196:197], v[212:213], v[196:197], v[216:217]
	v_pk_fma_f32 v[198:199], v[214:215], v[198:199], v[218:219]
	v_pk_mul_f32 v[196:197], v[196:197], s[82:83] op_sel_hi:[1,0]
	v_pk_mul_f32 v[198:199], v[198:199], s[82:83] op_sel_hi:[1,0]
	v_pk_fma_f32 v[76:77], v[76:77], 0.5, v[196:197] op_sel_hi:[1,0,1]
	v_pk_fma_f32 v[78:79], v[78:79], 0.5, v[198:199] op_sel_hi:[1,0,1]
	s_nop 0
	global_store_dwordx4 v132, v[76:79], s[58:59] offset:64 sc1
	global_load_dwordx4 v[196:199], v132, s[60:61] offset:576
	s_waitcnt vmcnt(16)
	v_pk_add_f32 v[200:201], v[200:201], v[220:221] op_sel_hi:[1,0] neg_lo:[0,1] neg_hi:[0,1]
	v_pk_add_f32 v[202:203], v[202:203], v[220:221] op_sel_hi:[1,0] neg_lo:[0,1] neg_hi:[0,1]
	v_pk_mul_f32 v[200:201], v[200:201], v[220:221] op_sel:[0,1] op_sel_hi:[1,1]
	v_pk_mul_f32 v[202:203], v[202:203], v[220:221] op_sel:[0,1] op_sel_hi:[1,1]
	v_pk_fma_f32 v[200:201], v[212:213], v[200:201], v[216:217]
	v_pk_fma_f32 v[202:203], v[214:215], v[202:203], v[218:219]
	v_pk_mul_f32 v[200:201], v[200:201], s[82:83] op_sel_hi:[1,0]
	v_pk_mul_f32 v[202:203], v[202:203], s[82:83] op_sel_hi:[1,0]
	v_pk_fma_f32 v[72:73], v[72:73], 0.5, v[200:201] op_sel_hi:[1,0,1]
	v_pk_fma_f32 v[74:75], v[74:75], 0.5, v[202:203] op_sel_hi:[1,0,1]
	s_nop 0
	global_store_dwordx4 v133, v[72:75], s[58:59] offset:64 sc1
	global_load_dwordx4 v[200:203], v133, s[60:61] offset:576
	s_waitcnt vmcnt(16)
	v_pk_add_f32 v[204:205], v[204:205], v[108:109] op_sel_hi:[1,0] neg_lo:[0,1] neg_hi:[0,1]
	v_pk_add_f32 v[206:207], v[206:207], v[108:109] op_sel_hi:[1,0] neg_lo:[0,1] neg_hi:[0,1]
	v_pk_mul_f32 v[204:205], v[204:205], v[108:109] op_sel:[0,1] op_sel_hi:[1,1]
	v_pk_mul_f32 v[206:207], v[206:207], v[108:109] op_sel:[0,1] op_sel_hi:[1,1]
	v_pk_fma_f32 v[204:205], v[212:213], v[204:205], v[216:217]
	v_pk_fma_f32 v[206:207], v[214:215], v[206:207], v[218:219]
	v_pk_mul_f32 v[204:205], v[204:205], s[82:83] op_sel_hi:[1,0]
	v_pk_mul_f32 v[206:207], v[206:207], s[82:83] op_sel_hi:[1,0]
	v_pk_fma_f32 v[68:69], v[68:69], 0.5, v[204:205] op_sel_hi:[1,0,1]
	v_pk_fma_f32 v[70:71], v[70:71], 0.5, v[206:207] op_sel_hi:[1,0,1]
	s_nop 0
	global_store_dwordx4 v134, v[68:71], s[58:59] offset:64 sc1
	global_load_dwordx4 v[204:207], v134, s[60:61] offset:576
	s_waitcnt vmcnt(16)
	v_pk_add_f32 v[208:209], v[208:209], v[110:111] op_sel_hi:[1,0] neg_lo:[0,1] neg_hi:[0,1]
	v_pk_add_f32 v[210:211], v[210:211], v[110:111] op_sel_hi:[1,0] neg_lo:[0,1] neg_hi:[0,1]
	v_pk_mul_f32 v[208:209], v[208:209], v[110:111] op_sel:[0,1] op_sel_hi:[1,1]
	v_pk_mul_f32 v[210:211], v[210:211], v[110:111] op_sel:[0,1] op_sel_hi:[1,1]
	v_pk_fma_f32 v[208:209], v[212:213], v[208:209], v[216:217]
	v_pk_fma_f32 v[210:211], v[214:215], v[210:211], v[218:219]
	v_pk_mul_f32 v[208:209], v[208:209], s[82:83] op_sel_hi:[1,0]
	v_pk_mul_f32 v[210:211], v[210:211], s[82:83] op_sel_hi:[1,0]
	v_pk_fma_f32 v[64:65], v[64:65], 0.5, v[208:209] op_sel_hi:[1,0,1]
	v_pk_fma_f32 v[66:67], v[66:67], 0.5, v[210:211] op_sel_hi:[1,0,1]
	s_nop 0
	global_store_dwordx4 v135, v[64:67], s[58:59] offset:64 sc1
	global_load_dwordx4 v[208:211], v135, s[60:61] offset:576
	s_waitcnt vmcnt(14)
	v_pk_add_f32 v[180:181], v[180:181], v[240:241] op_sel_hi:[1,0] neg_lo:[0,1] neg_hi:[0,1]
	v_pk_add_f32 v[182:183], v[182:183], v[240:241] op_sel_hi:[1,0] neg_lo:[0,1] neg_hi:[0,1]
	v_pk_mul_f32 v[180:181], v[180:181], v[240:241] op_sel:[0,1] op_sel_hi:[1,1]
	v_pk_mul_f32 v[182:183], v[182:183], v[240:241] op_sel:[0,1] op_sel_hi:[1,1]
	v_pk_fma_f32 v[180:181], v[232:233], v[180:181], v[236:237]
	v_pk_fma_f32 v[182:183], v[234:235], v[182:183], v[238:239]
	v_pk_mul_f32 v[180:181], v[180:181], s[82:83] op_sel_hi:[1,0]
	v_pk_mul_f32 v[182:183], v[182:183], s[82:83] op_sel_hi:[1,0]
	v_pk_fma_f32 v[28:29], v[28:29], 0.5, v[180:181] op_sel_hi:[1,0,1]
	v_pk_fma_f32 v[30:31], v[30:31], 0.5, v[182:183] op_sel_hi:[1,0,1]
	s_nop 0
	global_store_dwordx4 v112, v[28:31], s[58:59] offset:576 sc1
	s_waitcnt vmcnt(13)
	v_pk_add_f32 v[184:185], v[184:185], v[242:243] op_sel_hi:[1,0] neg_lo:[0,1] neg_hi:[0,1]
	v_pk_add_f32 v[186:187], v[186:187], v[242:243] op_sel_hi:[1,0] neg_lo:[0,1] neg_hi:[0,1]
	v_pk_mul_f32 v[184:185], v[184:185], v[242:243] op_sel:[0,1] op_sel_hi:[1,1]
	v_pk_mul_f32 v[186:187], v[186:187], v[242:243] op_sel:[0,1] op_sel_hi:[1,1]
	v_pk_fma_f32 v[184:185], v[232:233], v[184:185], v[236:237]
	v_pk_fma_f32 v[186:187], v[234:235], v[186:187], v[238:239]
	v_pk_mul_f32 v[184:185], v[184:185], s[82:83] op_sel_hi:[1,0]
	v_pk_mul_f32 v[186:187], v[186:187], s[82:83] op_sel_hi:[1,0]
	v_pk_fma_f32 v[24:25], v[24:25], 0.5, v[184:185] op_sel_hi:[1,0,1]
	v_pk_fma_f32 v[26:27], v[26:27], 0.5, v[186:187] op_sel_hi:[1,0,1]
	s_nop 0
	global_store_dwordx4 v113, v[24:27], s[58:59] offset:576 sc1
	s_waitcnt vmcnt(12)
	v_pk_add_f32 v[188:189], v[188:189], v[244:245] op_sel_hi:[1,0] neg_lo:[0,1] neg_hi:[0,1]
	v_pk_add_f32 v[190:191], v[190:191], v[244:245] op_sel_hi:[1,0] neg_lo:[0,1] neg_hi:[0,1]
	v_pk_mul_f32 v[188:189], v[188:189], v[244:245] op_sel:[0,1] op_sel_hi:[1,1]
	v_pk_mul_f32 v[190:191], v[190:191], v[244:245] op_sel:[0,1] op_sel_hi:[1,1]
	v_pk_fma_f32 v[188:189], v[232:233], v[188:189], v[236:237]
	v_pk_fma_f32 v[190:191], v[234:235], v[190:191], v[238:239]
	v_pk_mul_f32 v[188:189], v[188:189], s[82:83] op_sel_hi:[1,0]
	v_pk_mul_f32 v[190:191], v[190:191], s[82:83] op_sel_hi:[1,0]
	v_pk_fma_f32 v[20:21], v[20:21], 0.5, v[188:189] op_sel_hi:[1,0,1]
	v_pk_fma_f32 v[22:23], v[22:23], 0.5, v[190:191] op_sel_hi:[1,0,1]
	s_nop 0
	global_store_dwordx4 v130, v[20:23], s[58:59] offset:576 sc1
	s_waitcnt vmcnt(11)
	v_pk_add_f32 v[192:193], v[192:193], v[246:247] op_sel_hi:[1,0] neg_lo:[0,1] neg_hi:[0,1]
	v_pk_add_f32 v[194:195], v[194:195], v[246:247] op_sel_hi:[1,0] neg_lo:[0,1] neg_hi:[0,1]
	v_pk_mul_f32 v[192:193], v[192:193], v[246:247] op_sel:[0,1] op_sel_hi:[1,1]
	v_pk_mul_f32 v[194:195], v[194:195], v[246:247] op_sel:[0,1] op_sel_hi:[1,1]
	v_pk_fma_f32 v[192:193], v[232:233], v[192:193], v[236:237]
	v_pk_fma_f32 v[194:195], v[234:235], v[194:195], v[238:239]
	v_pk_mul_f32 v[192:193], v[192:193], s[82:83] op_sel_hi:[1,0]
	v_pk_mul_f32 v[194:195], v[194:195], s[82:83] op_sel_hi:[1,0]
	v_pk_fma_f32 v[16:17], v[16:17], 0.5, v[192:193] op_sel_hi:[1,0,1]
	v_pk_fma_f32 v[18:19], v[18:19], 0.5, v[194:195] op_sel_hi:[1,0,1]
	s_nop 0
	global_store_dwordx4 v131, v[16:19], s[58:59] offset:576 sc1
	s_waitcnt vmcnt(10)
	v_pk_add_f32 v[196:197], v[196:197], v[248:249] op_sel_hi:[1,0] neg_lo:[0,1] neg_hi:[0,1]
	v_pk_add_f32 v[198:199], v[198:199], v[248:249] op_sel_hi:[1,0] neg_lo:[0,1] neg_hi:[0,1]
	v_pk_mul_f32 v[196:197], v[196:197], v[248:249] op_sel:[0,1] op_sel_hi:[1,1]
	v_pk_mul_f32 v[198:199], v[198:199], v[248:249] op_sel:[0,1] op_sel_hi:[1,1]
	v_pk_fma_f32 v[196:197], v[232:233], v[196:197], v[236:237]
	v_pk_fma_f32 v[198:199], v[234:235], v[198:199], v[238:239]
	v_pk_mul_f32 v[196:197], v[196:197], s[82:83] op_sel_hi:[1,0]
	v_pk_mul_f32 v[198:199], v[198:199], s[82:83] op_sel_hi:[1,0]
	v_pk_fma_f32 v[12:13], v[12:13], 0.5, v[196:197] op_sel_hi:[1,0,1]
	v_pk_fma_f32 v[14:15], v[14:15], 0.5, v[198:199] op_sel_hi:[1,0,1]
	s_nop 0
	global_store_dwordx4 v132, v[12:15], s[58:59] offset:576 sc1
	s_waitcnt vmcnt(9)
	v_pk_add_f32 v[200:201], v[200:201], v[220:221] op_sel_hi:[1,0] neg_lo:[0,1] neg_hi:[0,1]
	v_pk_add_f32 v[202:203], v[202:203], v[220:221] op_sel_hi:[1,0] neg_lo:[0,1] neg_hi:[0,1]
	v_pk_mul_f32 v[200:201], v[200:201], v[220:221] op_sel:[0,1] op_sel_hi:[1,1]
	v_pk_mul_f32 v[202:203], v[202:203], v[220:221] op_sel:[0,1] op_sel_hi:[1,1]
	v_pk_fma_f32 v[200:201], v[232:233], v[200:201], v[236:237]
	v_pk_fma_f32 v[202:203], v[234:235], v[202:203], v[238:239]
	v_pk_mul_f32 v[200:201], v[200:201], s[82:83] op_sel_hi:[1,0]
	v_pk_mul_f32 v[202:203], v[202:203], s[82:83] op_sel_hi:[1,0]
	v_pk_fma_f32 v[8:9], v[8:9], 0.5, v[200:201] op_sel_hi:[1,0,1]
	v_pk_fma_f32 v[10:11], v[10:11], 0.5, v[202:203] op_sel_hi:[1,0,1]
	s_nop 0
	global_store_dwordx4 v133, v[8:11], s[58:59] offset:576 sc1
	s_waitcnt vmcnt(8)
	v_pk_add_f32 v[204:205], v[204:205], v[108:109] op_sel_hi:[1,0] neg_lo:[0,1] neg_hi:[0,1]
	v_pk_add_f32 v[206:207], v[206:207], v[108:109] op_sel_hi:[1,0] neg_lo:[0,1] neg_hi:[0,1]
	v_pk_mul_f32 v[204:205], v[204:205], v[108:109] op_sel:[0,1] op_sel_hi:[1,1]
	v_pk_mul_f32 v[206:207], v[206:207], v[108:109] op_sel:[0,1] op_sel_hi:[1,1]
	v_pk_fma_f32 v[204:205], v[232:233], v[204:205], v[236:237]
	v_pk_fma_f32 v[206:207], v[234:235], v[206:207], v[238:239]
	v_pk_mul_f32 v[204:205], v[204:205], s[82:83] op_sel_hi:[1,0]
	v_pk_mul_f32 v[206:207], v[206:207], s[82:83] op_sel_hi:[1,0]
	v_pk_fma_f32 v[4:5], v[4:5], 0.5, v[204:205] op_sel_hi:[1,0,1]
	v_pk_fma_f32 v[6:7], v[6:7], 0.5, v[206:207] op_sel_hi:[1,0,1]
	s_nop 0
	global_store_dwordx4 v134, v[4:7], s[58:59] offset:576 sc1
	s_waitcnt vmcnt(7)
	v_pk_add_f32 v[208:209], v[208:209], v[110:111] op_sel_hi:[1,0] neg_lo:[0,1] neg_hi:[0,1]
	v_pk_add_f32 v[210:211], v[210:211], v[110:111] op_sel_hi:[1,0] neg_lo:[0,1] neg_hi:[0,1]
	v_pk_mul_f32 v[208:209], v[208:209], v[110:111] op_sel:[0,1] op_sel_hi:[1,1]
	v_pk_mul_f32 v[210:211], v[210:211], v[110:111] op_sel:[0,1] op_sel_hi:[1,1]
	v_pk_fma_f32 v[208:209], v[232:233], v[208:209], v[236:237]
	v_pk_fma_f32 v[210:211], v[234:235], v[210:211], v[238:239]
	v_pk_mul_f32 v[208:209], v[208:209], s[82:83] op_sel_hi:[1,0]
	v_pk_mul_f32 v[210:211], v[210:211], s[82:83] op_sel_hi:[1,0]
	v_pk_fma_f32 v[0:1], v[0:1], 0.5, v[208:209] op_sel_hi:[1,0,1]
	v_pk_fma_f32 v[2:3], v[2:3], 0.5, v[210:211] op_sel_hi:[1,0,1]
	s_nop 0
	global_store_dwordx4 v135, v[0:3], s[58:59] offset:576 sc1
	s_branch .Lepi_A_join
.Lepi_A_nostats:
	s_mov_b64 s[40:41], exec
	v_lshl_add_u32 v112, v160, 2, v137
	v_lshl_add_u32 v113, v164, 2, v137
	v_lshl_add_u32 v130, v166, 2, v137
	v_lshl_add_u32 v131, v168, 2, v137
	v_lshl_add_u32 v132, v162, 2, v137
	v_lshl_add_u32 v133, v170, 2, v137
	v_lshl_add_u32 v134, v172, 2, v137
	v_lshl_add_u32 v135, v174, 2, v137
	global_load_dwordx4 v[180:183], v112, s[60:61]
	global_load_dwordx4 v[184:187], v113, s[60:61]
	global_load_dwordx4 v[188:191], v130, s[60:61]
	global_load_dwordx4 v[192:195], v131, s[60:61]
	global_load_dwordx4 v[196:199], v132, s[60:61]
	global_load_dwordx4 v[200:203], v133, s[60:61]
	global_load_dwordx4 v[204:207], v134, s[60:61]
	global_load_dwordx4 v[208:211], v135, s[60:61]
	s_waitcnt vmcnt(7)
	v_pk_mul_f32 v[180:181], v[180:181], s[82:83] op_sel_hi:[1,0]
	v_pk_mul_f32 v[182:183], v[182:183], s[82:83] op_sel_hi:[1,0]
	v_pk_fma_f32 v[138:139], v[138:139], 0.5, v[180:181] op_sel_hi:[1,0,1]
	v_pk_fma_f32 v[140:141], v[140:141], 0.5, v[182:183] op_sel_hi:[1,0,1]
	s_nop 0
	global_store_dwordx4 v112, v[138:141], s[58:59] sc1
	global_load_dwordx4 v[180:183], v112, s[60:61] offset:512
	s_waitcnt vmcnt(8)
	v_pk_mul_f32 v[184:185], v[184:185], s[82:83] op_sel_hi:[1,0]
	v_pk_mul_f32 v[186:187], v[186:187], s[82:83] op_sel_hi:[1,0]
	v_pk_fma_f32 v[126:127], v[126:127], 0.5, v[184:185] op_sel_hi:[1,0,1]
	v_pk_fma_f32 v[128:129], v[128:129], 0.5, v[186:187] op_sel_hi:[1,0,1]
	s_nop 0
	global_store_dwordx4 v113, v[126:129], s[58:59] sc1
	global_load_dwordx4 v[184:187], v113, s[60:61] offset:512
	s_waitcnt vmcnt(9)
	v_pk_mul_f32 v[188:189], v[188:189], s[82:83] op_sel_hi:[1,0]
	v_pk_mul_f32 v[190:191], v[190:191], s[82:83] op_sel_hi:[1,0]
	v_pk_fma_f32 v[122:123], v[122:123], 0.5, v[188:189] op_sel_hi:[1,0,1]
	v_pk_fma_f32 v[124:125], v[124:125], 0.5, v[190:191] op_sel_hi:[1,0,1]
	s_nop 0
	global_store_dwordx4 v130, v[122:125], s[58:59] sc1
	global_load_dwordx4 v[188:191], v130, s[60:61] offset:512
	s_waitcnt vmcnt(10)
	v_pk_mul_f32 v[192:193], v[192:193], s[82:83] op_sel_hi:[1,0]
	v_pk_mul_f32 v[194:195], v[194:195], s[82:83] op_sel_hi:[1,0]
	v_pk_fma_f32 v[118:119], v[118:119], 0.5, v[192:193] op_sel_hi:[1,0,1]
	v_pk_fma_f32 v[120:121], v[120:121], 0.5, v[194:195] op_sel_hi:[1,0,1]
	s_nop 0
	global_store_dwordx4 v131, v[118:121], s[58:59] sc1
	global_load_dwordx4 v[192:195], v131, s[60:61] offset:512
	s_waitcnt vmcnt(11)
	v_pk_mul_f32 v[196:197], v[196:197], s[82:83] op_sel_hi:[1,0]
	v_pk_mul_f32 v[198:199], v[198:199], s[82:83] op_sel_hi:[1,0]
	v_pk_fma_f32 v[114:115], v[114:115], 0.5, v[196:197] op_sel_hi:[1,0,1]
	v_pk_fma_f32 v[116:117], v[116:117], 0.5, v[198:199] op_sel_hi:[1,0,1]
	s_nop 0
	global_store_dwordx4 v132, v[114:117], s[58:59] sc1
	global_load_dwordx4 v[196:199], v132, s[60:61] offset:512
	s_waitcnt vmcnt(12)
	v_pk_mul_f32 v[200:201], v[200:201], s[82:83] op_sel_hi:[1,0]
	v_pk_mul_f32 v[202:203], v[202:203], s[82:83] op_sel_hi:[1,0]
	v_pk_fma_f32 v[104:105], v[104:105], 0.5, v[200:201] op_sel_hi:[1,0,1]
	v_pk_fma_f32 v[106:107], v[106:107], 0.5, v[202:203] op_sel_hi:[1,0,1]
	s_nop 0
	global_store_dwordx4 v133, v[104:107], s[58:59] sc1
	global_load_dwordx4 v[200:203], v133, s[60:61] offset:512
	s_waitcnt vmcnt(13)
	v_pk_mul_f32 v[204:205], v[204:205], s[82:83] op_sel_hi:[1,0]
	v_pk_mul_f32 v[206:207], v[206:207], s[82:83] op_sel_hi:[1,0]
	v_pk_fma_f32 v[100:101], v[100:101], 0.5, v[204:205] op_sel_hi:[1,0,1]
	v_pk_fma_f32 v[102:103], v[102:103], 0.5, v[206:207] op_sel_hi:[1,0,1]
	s_nop 0
	global_store_dwordx4 v134, v[100:103], s[58:59] sc1
	global_load_dwordx4 v[204:207], v134, s[60:61] offset:512
	s_waitcnt vmcnt(14)
	v_pk_mul_f32 v[208:209], v[208:209], s[82:83] op_sel_hi:[1,0]
	v_pk_mul_f32 v[210:211], v[210:211], s[82:83] op_sel_hi:[1,0]
	v_pk_fma_f32 v[96:97], v[96:97], 0.5, v[208:209] op_sel_hi:[1,0,1]
	v_pk_fma_f32 v[98:99], v[98:99], 0.5, v[210:211] op_sel_hi:[1,0,1]
	s_nop 0
	global_store_dwordx4 v135, v[96:99], s[58:59] sc1
	global_load_dwordx4 v[208:211], v135, s[60:61] offset:512
	s_waitcnt vmcnt(14)
	v_pk_mul_f32 v[180:181], v[180:181], s[82:83] op_sel_hi:[1,0]
	v_pk_mul_f32 v[182:183], v[182:183], s[82:83] op_sel_hi:[1,0]
	v_pk_fma_f32 v[60:61], v[60:61], 0.5, v[180:181] op_sel_hi:[1,0,1]
	v_pk_fma_f32 v[62:63], v[62:63], 0.5, v[182:183] op_sel_hi:[1,0,1]
	s_nop 0
	global_store_dwordx4 v112, v[60:63], s[58:59] offset:512 sc1
	global_load_dwordx4 v[180:183], v112, s[60:61] offset:64
	s_waitcnt vmcnt(14)
	v_pk_mul_f32 v[184:185], v[184:185], s[82:83] op_sel_hi:[1,0]
	v_pk_mul_f32 v[186:187], v[186:187], s[82:83] op_sel_hi:[1,0]
	v_pk_fma_f32 v[56:57], v[56:57], 0.5, v[184:185] op_sel_hi:[1,0,1]
	v_pk_fma_f32 v[58:59], v[58:59], 0.5, v[186:187] op_sel_hi:[1,0,1]
	s_nop 0
	global_store_dwordx4 v113, v[56:59], s[58:59] offset:512 sc1
	global_load_dwordx4 v[184:187], v113, s[60:61] offset:64
	s_waitcnt vmcnt(14)
	v_pk_mul_f32 v[188:189], v[188:189], s[82:83] op_sel_hi:[1,0]
	v_pk_mul_f32 v[190:191], v[190:191], s[82:83] op_sel_hi:[1,0]
	v_pk_fma_f32 v[52:53], v[52:53], 0.5, v[188:189] op_sel_hi:[1,0,1]
	v_pk_fma_f32 v[54:55], v[54:55], 0.5, v[190:191] op_sel_hi:[1,0,1]
	s_nop 0
	global_store_dwordx4 v130, v[52:55], s[58:59] offset:512 sc1
	global_load_dwordx4 v[188:191], v130, s[60:61] offset:64
	s_waitcnt vmcnt(14)
	v_pk_mul_f32 v[192:193], v[192:193], s[82:83] op_sel_hi:[1,0]
	v_pk_mul_f32 v[194:195], v[194:195], s[82:83] op_sel_hi:[1,0]
	v_pk_fma_f32 v[48:49], v[48:49], 0.5, v[192:193] op_sel_hi:[1,0,1]
	v_pk_fma_f32 v[50:51], v[50:51], 0.5, v[194:195] op_sel_hi:[1,0,1]
	s_nop 0
	global_store_dwordx4 v131, v[48:51], s[58:59] offset:512 sc1
	global_load_dwordx4 v[192:195], v131, s[60:61] offset:64
	s_waitcnt vmcnt(14)
	v_pk_mul_f32 v[196:197], v[196:197], s[82:83] op_sel_hi:[1,0]
	v_pk_mul_f32 v[198:199], v[198:199], s[82:83] op_sel_hi:[1,0]
	v_pk_fma_f32 v[44:45], v[44:45], 0.5, v[196:197] op_sel_hi:[1,0,1]
	v_pk_fma_f32 v[46:47], v[46:47], 0.5, v[198:199] op_sel_hi:[1,0,1]
	s_nop 0
	global_store_dwordx4 v132, v[44:47], s[58:59] offset:512 sc1
	global_load_dwordx4 v[196:199], v132, s[60:61] offset:64
	s_waitcnt vmcnt(14)
	v_pk_mul_f32 v[200:201], v[200:201], s[82:83] op_sel_hi:[1,0]
	v_pk_mul_f32 v[202:203], v[202:203], s[82:83] op_sel_hi:[1,0]
	v_pk_fma_f32 v[40:41], v[40:41], 0.5, v[200:201] op_sel_hi:[1,0,1]
	v_pk_fma_f32 v[42:43], v[42:43], 0.5, v[202:203] op_sel_hi:[1,0,1]
	s_nop 0
	global_store_dwordx4 v133, v[40:43], s[58:59] offset:512 sc1
	global_load_dwordx4 v[200:203], v133, s[60:61] offset:64
	s_waitcnt vmcnt(14)
	v_pk_mul_f32 v[204:205], v[204:205], s[82:83] op_sel_hi:[1,0]
	v_pk_mul_f32 v[206:207], v[206:207], s[82:83] op_sel_hi:[1,0]
	v_pk_fma_f32 v[36:37], v[36:37], 0.5, v[204:205] op_sel_hi:[1,0,1]
	v_pk_fma_f32 v[38:39], v[38:39], 0.5, v[206:207] op_sel_hi:[1,0,1]
	s_nop 0
	global_store_dwordx4 v134, v[36:39], s[58:59] offset:512 sc1
	global_load_dwordx4 v[204:207], v134, s[60:61] offset:64
	s_waitcnt vmcnt(14)
	v_pk_mul_f32 v[208:209], v[208:209], s[82:83] op_sel_hi:[1,0]
	v_pk_mul_f32 v[210:211], v[210:211], s[82:83] op_sel_hi:[1,0]
	v_pk_fma_f32 v[32:33], v[32:33], 0.5, v[208:209] op_sel_hi:[1,0,1]
	v_pk_fma_f32 v[34:35], v[34:35], 0.5, v[210:211] op_sel_hi:[1,0,1]
	s_nop 0
	global_store_dwordx4 v135, v[32:35], s[58:59] offset:512 sc1
	global_load_dwordx4 v[208:211], v135, s[60:61] offset:64
	s_waitcnt vmcnt(14)
	v_pk_mul_f32 v[180:181], v[180:181], s[82:83] op_sel_hi:[1,0]
	v_pk_mul_f32 v[182:183], v[182:183], s[82:83] op_sel_hi:[1,0]
	v_pk_fma_f32 v[92:93], v[92:93], 0.5, v[180:181] op_sel_hi:[1,0,1]
	v_pk_fma_f32 v[94:95], v[94:95], 0.5, v[182:183] op_sel_hi:[1,0,1]
	s_nop 0
	global_store_dwordx4 v112, v[92:95], s[58:59] offset:64 sc1
	global_load_dwordx4 v[180:183], v112, s[60:61] offset:576
	s_waitcnt vmcnt(14)
	v_pk_mul_f32 v[184:185], v[184:185], s[82:83] op_sel_hi:[1,0]
	v_pk_mul_f32 v[186:187], v[186:187], s[82:83] op_sel_hi:[1,0]
	v_pk_fma_f32 v[88:89], v[88:89], 0.5, v[184:185] op_sel_hi:[1,0,1]
	v_pk_fma_f32 v[90:91], v[90:91], 0.5, v[186:187] op_sel_hi:[1,0,1]
	s_nop 0
	global_store_dwordx4 v113, v[88:91], s[58:59] offset:64 sc1
	global_load_dwordx4 v[184:187], v113, s[60:61] offset:576
	s_waitcnt vmcnt(14)
	v_pk_mul_f32 v[188:189], v[188:189], s[82:83] op_sel_hi:[1,0]
	v_pk_mul_f32 v[190:191], v[190:191], s[82:83] op_sel_hi:[1,0]
	v_pk_fma_f32 v[84:85], v[84:85], 0.5, v[188:189] op_sel_hi:[1,0,1]
	v_pk_fma_f32 v[86:87], v[86:87], 0.5, v[190:191] op_sel_hi:[1,0,1]
	s_nop 0
	global_store_dwordx4 v130, v[84:87], s[58:59] offset:64 sc1
	global_load_dwordx4 v[188:191], v130, s[60:61] offset:576
	s_waitcnt vmcnt(14)
	v_pk_mul_f32 v[192:193], v[192:193], s[82:83] op_sel_hi:[1,0]
	v_pk_mul_f32 v[194:195], v[194:195], s[82:83] op_sel_hi:[1,0]
	v_pk_fma_f32 v[80:81], v[80:81], 0.5, v[192:193] op_sel_hi:[1,0,1]
	v_pk_fma_f32 v[82:83], v[82:83], 0.5, v[194:195] op_sel_hi:[1,0,1]
	s_nop 0
	global_store_dwordx4 v131, v[80:83], s[58:59] offset:64 sc1
	global_load_dwordx4 v[192:195], v131, s[60:61] offset:576
	s_waitcnt vmcnt(14)
	v_pk_mul_f32 v[196:197], v[196:197], s[82:83] op_sel_hi:[1,0]
	v_pk_mul_f32 v[198:199], v[198:199], s[82:83] op_sel_hi:[1,0]
	v_pk_fma_f32 v[76:77], v[76:77], 0.5, v[196:197] op_sel_hi:[1,0,1]
	v_pk_fma_f32 v[78:79], v[78:79], 0.5, v[198:199] op_sel_hi:[1,0,1]
	s_nop 0
	global_store_dwordx4 v132, v[76:79], s[58:59] offset:64 sc1
	global_load_dwordx4 v[196:199], v132, s[60:61] offset:576
	s_waitcnt vmcnt(14)
	v_pk_mul_f32 v[200:201], v[200:201], s[82:83] op_sel_hi:[1,0]
	v_pk_mul_f32 v[202:203], v[202:203], s[82:83] op_sel_hi:[1,0]
	v_pk_fma_f32 v[72:73], v[72:73], 0.5, v[200:201] op_sel_hi:[1,0,1]
	v_pk_fma_f32 v[74:75], v[74:75], 0.5, v[202:203] op_sel_hi:[1,0,1]
	s_nop 0
	global_store_dwordx4 v133, v[72:75], s[58:59] offset:64 sc1
	global_load_dwordx4 v[200:203], v133, s[60:61] offset:576
	s_waitcnt vmcnt(14)
	v_pk_mul_f32 v[204:205], v[204:205], s[82:83] op_sel_hi:[1,0]
	v_pk_mul_f32 v[206:207], v[206:207], s[82:83] op_sel_hi:[1,0]
	v_pk_fma_f32 v[68:69], v[68:69], 0.5, v[204:205] op_sel_hi:[1,0,1]
	v_pk_fma_f32 v[70:71], v[70:71], 0.5, v[206:207] op_sel_hi:[1,0,1]
	s_nop 0
	global_store_dwordx4 v134, v[68:71], s[58:59] offset:64 sc1
	global_load_dwordx4 v[204:207], v134, s[60:61] offset:576
	s_waitcnt vmcnt(14)
	v_pk_mul_f32 v[208:209], v[208:209], s[82:83] op_sel_hi:[1,0]
	v_pk_mul_f32 v[210:211], v[210:211], s[82:83] op_sel_hi:[1,0]
	v_pk_fma_f32 v[64:65], v[64:65], 0.5, v[208:209] op_sel_hi:[1,0,1]
	v_pk_fma_f32 v[66:67], v[66:67], 0.5, v[210:211] op_sel_hi:[1,0,1]
	s_nop 0
	global_store_dwordx4 v135, v[64:67], s[58:59] offset:64 sc1
	global_load_dwordx4 v[208:211], v135, s[60:61] offset:576
	s_waitcnt vmcnt(14)
	v_pk_mul_f32 v[180:181], v[180:181], s[82:83] op_sel_hi:[1,0]
	v_pk_mul_f32 v[182:183], v[182:183], s[82:83] op_sel_hi:[1,0]
	v_pk_fma_f32 v[28:29], v[28:29], 0.5, v[180:181] op_sel_hi:[1,0,1]
	v_pk_fma_f32 v[30:31], v[30:31], 0.5, v[182:183] op_sel_hi:[1,0,1]
	s_nop 0
	global_store_dwordx4 v112, v[28:31], s[58:59] offset:576 sc1
	s_waitcnt vmcnt(13)
	v_pk_mul_f32 v[184:185], v[184:185], s[82:83] op_sel_hi:[1,0]
	v_pk_mul_f32 v[186:187], v[186:187], s[82:83] op_sel_hi:[1,0]
	v_pk_fma_f32 v[24:25], v[24:25], 0.5, v[184:185] op_sel_hi:[1,0,1]
	v_pk_fma_f32 v[26:27], v[26:27], 0.5, v[186:187] op_sel_hi:[1,0,1]
	s_nop 0
	global_store_dwordx4 v113, v[24:27], s[58:59] offset:576 sc1
	s_waitcnt vmcnt(12)
	v_pk_mul_f32 v[188:189], v[188:189], s[82:83] op_sel_hi:[1,0]
	v_pk_mul_f32 v[190:191], v[190:191], s[82:83] op_sel_hi:[1,0]
	v_pk_fma_f32 v[20:21], v[20:21], 0.5, v[188:189] op_sel_hi:[1,0,1]
	v_pk_fma_f32 v[22:23], v[22:23], 0.5, v[190:191] op_sel_hi:[1,0,1]
	s_nop 0
	global_store_dwordx4 v130, v[20:23], s[58:59] offset:576 sc1
	s_waitcnt vmcnt(11)
	v_pk_mul_f32 v[192:193], v[192:193], s[82:83] op_sel_hi:[1,0]
	v_pk_mul_f32 v[194:195], v[194:195], s[82:83] op_sel_hi:[1,0]
	v_pk_fma_f32 v[16:17], v[16:17], 0.5, v[192:193] op_sel_hi:[1,0,1]
	v_pk_fma_f32 v[18:19], v[18:19], 0.5, v[194:195] op_sel_hi:[1,0,1]
	s_nop 0
	global_store_dwordx4 v131, v[16:19], s[58:59] offset:576 sc1
	s_waitcnt vmcnt(10)
	v_pk_mul_f32 v[196:197], v[196:197], s[82:83] op_sel_hi:[1,0]
	v_pk_mul_f32 v[198:199], v[198:199], s[82:83] op_sel_hi:[1,0]
	v_pk_fma_f32 v[12:13], v[12:13], 0.5, v[196:197] op_sel_hi:[1,0,1]
	v_pk_fma_f32 v[14:15], v[14:15], 0.5, v[198:199] op_sel_hi:[1,0,1]
	s_nop 0
	global_store_dwordx4 v132, v[12:15], s[58:59] offset:576 sc1
	s_waitcnt vmcnt(9)
	v_pk_mul_f32 v[200:201], v[200:201], s[82:83] op_sel_hi:[1,0]
	v_pk_mul_f32 v[202:203], v[202:203], s[82:83] op_sel_hi:[1,0]
	v_pk_fma_f32 v[8:9], v[8:9], 0.5, v[200:201] op_sel_hi:[1,0,1]
	v_pk_fma_f32 v[10:11], v[10:11], 0.5, v[202:203] op_sel_hi:[1,0,1]
	s_nop 0
	global_store_dwordx4 v133, v[8:11], s[58:59] offset:576 sc1
	s_waitcnt vmcnt(8)
	v_pk_mul_f32 v[204:205], v[204:205], s[82:83] op_sel_hi:[1,0]
	v_pk_mul_f32 v[206:207], v[206:207], s[82:83] op_sel_hi:[1,0]
	v_pk_fma_f32 v[4:5], v[4:5], 0.5, v[204:205] op_sel_hi:[1,0,1]
	v_pk_fma_f32 v[6:7], v[6:7], 0.5, v[206:207] op_sel_hi:[1,0,1]
	s_nop 0
	global_store_dwordx4 v134, v[4:7], s[58:59] offset:576 sc1
	s_waitcnt vmcnt(7)
	v_pk_mul_f32 v[208:209], v[208:209], s[82:83] op_sel_hi:[1,0]
	v_pk_mul_f32 v[210:211], v[210:211], s[82:83] op_sel_hi:[1,0]
	v_pk_fma_f32 v[0:1], v[0:1], 0.5, v[208:209] op_sel_hi:[1,0,1]
	v_pk_fma_f32 v[2:3], v[2:3], 0.5, v[210:211] op_sel_hi:[1,0,1]
	s_nop 0
	global_store_dwordx4 v135, v[0:3], s[58:59] offset:576 sc1
.Lepi_A_join:
	s_and_b64 vcc, exec, s[38:39]
	s_mov_b64 s[38:39], -1

.LBB0_1086:
	v_lshl_add_u32 v248, s60, 8, v138
	v_lshl_or_b32 v249, s75, 8, v139
	v_lshlrev_b32_e32 v248, 3, v248
	v_lshlrev_b32_e32 v249, 2, v249
	s_ashr_i32 s61, s60, 31
	s_lshl_b64 s[28:29], s[60:61], 20
	v_readlane_b32 s4, v252, 0
	v_readlane_b32 s5, v252, 1
	v_readlane_b32 s6, v252, 2
	v_readlane_b32 s7, v252, 3
	v_readlane_b32 s8, v252, 4
	v_readlane_b32 s9, v252, 5
	v_readlane_b32 s10, v252, 6
	v_readlane_b32 s11, v252, 7
	v_readlane_b32 s12, v252, 8
	v_readlane_b32 s13, v252, 9
	v_readlane_b32 s14, v252, 10
	v_readlane_b32 s15, v252, 11
	v_readlane_b32 s16, v252, 12
	v_readlane_b32 s17, v252, 13
	s_mov_b64 s[4:5], s[8:9]
	v_readlane_b32 s18, v252, 14
	v_readlane_b32 s19, v252, 15
	s_mov_b64 s[6:7], s[10:11]
	s_mov_b64 s[8:9], s[12:13]
	s_mov_b64 s[12:13], s[16:17]
	s_add_u32 s60, s12, s28
	s_addc_u32 s61, s13, s29
	s_mov_b64 s[14:15], s[18:19]
	global_load_dwordx2 v[208:209], v248, s[92:93]
	global_load_dwordx2 v[210:211], v248, s[92:93] offset:128
	global_load_dwordx2 v[212:213], v248, s[92:93] offset:256
	global_load_dwordx2 v[214:215], v248, s[92:93] offset:384
	global_load_dwordx2 v[216:217], v248, s[92:93] offset:1024
	global_load_dwordx2 v[218:219], v248, s[92:93] offset:1152
	global_load_dwordx2 v[220:221], v248, s[92:93] offset:1280
	global_load_dwordx2 v[230:231], v248, s[92:93] offset:1408
	global_load_dwordx4 v[232:235], v249, s[44:45]
	global_load_dwordx4 v[236:239], v249, s[46:47]
	v_add_u32_e32 v124, v140, v249
	v_add_u32_e32 v125, v164, v249
	v_add_u32_e32 v126, v166, v249
	v_add_u32_e32 v127, v168, v249
	v_add_u32_e32 v128, v156, v249
	v_add_u32_e32 v129, v158, v249
	v_add_u32_e32 v130, v160, v249
	v_add_u32_e32 v131, v162, v249
	global_load_dwordx4 v[174:177], v124, s[60:61]
	global_load_dwordx4 v[178:181], v125, s[60:61]
	global_load_dwordx4 v[182:185], v126, s[60:61]
	global_load_dwordx4 v[186:189], v127, s[60:61]
	global_load_dwordx4 v[190:193], v128, s[60:61]
	global_load_dwordx4 v[194:197], v129, s[60:61]
	global_load_dwordx4 v[200:203], v130, s[60:61]
	global_load_dwordx4 v[204:207], v131, s[60:61]
	global_load_dwordx4 v[240:243], v249, s[44:45] offset:512
	global_load_dwordx4 v[244:247], v249, s[46:47] offset:512
	s_waitcnt vmcnt(9)
	v_pk_add_f32 v[174:175], v[174:175], v[208:209] op_sel_hi:[1,0] neg_lo:[0,1] neg_hi:[0,1]
	v_pk_add_f32 v[176:177], v[176:177], v[208:209] op_sel_hi:[1,0] neg_lo:[0,1] neg_hi:[0,1]
	v_pk_mul_f32 v[174:175], v[174:175], v[208:209] op_sel:[0,1] op_sel_hi:[1,1]
	v_pk_mul_f32 v[176:177], v[176:177], v[208:209] op_sel:[0,1] op_sel_hi:[1,1]
	v_pk_fma_f32 v[174:175], v[232:233], v[174:175], v[236:237]
	v_pk_fma_f32 v[176:177], v[234:235], v[176:177], v[238:239]
	v_pk_fma_f32 v[132:133], v[174:175], s[82:83], v[132:133] op_sel_hi:[1,0,1]
	v_pk_fma_f32 v[134:135], v[176:177], s[82:83], v[134:135] op_sel_hi:[1,0,1]
	s_nop 0
	global_store_dwordx4 v124, v[132:135], s[60:61] sc1
	global_load_dwordx4 v[174:177], v124, s[60:61] offset:512
	s_waitcnt vmcnt(10)
	v_pk_add_f32 v[178:179], v[178:179], v[210:211] op_sel_hi:[1,0] neg_lo:[0,1] neg_hi:[0,1]
	v_pk_add_f32 v[180:181], v[180:181], v[210:211] op_sel_hi:[1,0] neg_lo:[0,1] neg_hi:[0,1]
	v_pk_mul_f32 v[178:179], v[178:179], v[210:211] op_sel:[0,1] op_sel_hi:[1,1]
	v_pk_mul_f32 v[180:181], v[180:181], v[210:211] op_sel:[0,1] op_sel_hi:[1,1]
	v_pk_fma_f32 v[178:179], v[232:233], v[178:179], v[236:237]
	v_pk_fma_f32 v[180:181], v[234:235], v[180:181], v[238:239]
	v_pk_fma_f32 v[120:121], v[178:179], s[82:83], v[120:121] op_sel_hi:[1,0,1]
	v_pk_fma_f32 v[122:123], v[180:181], s[82:83], v[122:123] op_sel_hi:[1,0,1]
	s_nop 0
	global_store_dwordx4 v125, v[120:123], s[60:61] sc1
	global_load_dwordx4 v[178:181], v125, s[60:61] offset:512
	s_waitcnt vmcnt(11)
	v_pk_add_f32 v[182:183], v[182:183], v[212:213] op_sel_hi:[1,0] neg_lo:[0,1] neg_hi:[0,1]
	v_pk_add_f32 v[184:185], v[184:185], v[212:213] op_sel_hi:[1,0] neg_lo:[0,1] neg_hi:[0,1]
	v_pk_mul_f32 v[182:183], v[182:183], v[212:213] op_sel:[0,1] op_sel_hi:[1,1]
	v_pk_mul_f32 v[184:185], v[184:185], v[212:213] op_sel:[0,1] op_sel_hi:[1,1]
	v_pk_fma_f32 v[182:183], v[232:233], v[182:183], v[236:237]
	v_pk_fma_f32 v[184:185], v[234:235], v[184:185], v[238:239]
	v_pk_fma_f32 v[116:117], v[182:183], s[82:83], v[116:117] op_sel_hi:[1,0,1]
	v_pk_fma_f32 v[118:119], v[184:185], s[82:83], v[118:119] op_sel_hi:[1,0,1]
	s_nop 0
	global_store_dwordx4 v126, v[116:119], s[60:61] sc1
	global_load_dwordx4 v[182:185], v126, s[60:61] offset:512
	s_waitcnt vmcnt(12)
	v_pk_add_f32 v[186:187], v[186:187], v[214:215] op_sel_hi:[1,0] neg_lo:[0,1] neg_hi:[0,1]
	v_pk_add_f32 v[188:189], v[188:189], v[214:215] op_sel_hi:[1,0] neg_lo:[0,1] neg_hi:[0,1]
	v_pk_mul_f32 v[186:187], v[186:187], v[214:215] op_sel:[0,1] op_sel_hi:[1,1]
	v_pk_mul_f32 v[188:189], v[188:189], v[214:215] op_sel:[0,1] op_sel_hi:[1,1]
	v_pk_fma_f32 v[186:187], v[232:233], v[186:187], v[236:237]
	v_pk_fma_f32 v[188:189], v[234:235], v[188:189], v[238:239]
	v_pk_fma_f32 v[112:113], v[186:187], s[82:83], v[112:113] op_sel_hi:[1,0,1]
	v_pk_fma_f32 v[114:115], v[188:189], s[82:83], v[114:115] op_sel_hi:[1,0,1]
	s_nop 0
	global_store_dwordx4 v127, v[112:115], s[60:61] sc1
	global_load_dwordx4 v[186:189], v127, s[60:61] offset:512
	s_waitcnt vmcnt(13)
	v_pk_add_f32 v[190:191], v[190:191], v[216:217] op_sel_hi:[1,0] neg_lo:[0,1] neg_hi:[0,1]
	v_pk_add_f32 v[192:193], v[192:193], v[216:217] op_sel_hi:[1,0] neg_lo:[0,1] neg_hi:[0,1]
	v_pk_mul_f32 v[190:191], v[190:191], v[216:217] op_sel:[0,1] op_sel_hi:[1,1]
	v_pk_mul_f32 v[192:193], v[192:193], v[216:217] op_sel:[0,1] op_sel_hi:[1,1]
	v_pk_fma_f32 v[190:191], v[232:233], v[190:191], v[236:237]
	v_pk_fma_f32 v[192:193], v[234:235], v[192:193], v[238:239]
	v_pk_fma_f32 v[108:109], v[190:191], s[82:83], v[108:109] op_sel_hi:[1,0,1]
	v_pk_fma_f32 v[110:111], v[192:193], s[82:83], v[110:111] op_sel_hi:[1,0,1]
	s_nop 0
	global_store_dwordx4 v128, v[108:111], s[60:61] sc1
	global_load_dwordx4 v[190:193], v128, s[60:61] offset:512
	s_waitcnt vmcnt(14)
	v_pk_add_f32 v[194:195], v[194:195], v[218:219] op_sel_hi:[1,0] neg_lo:[0,1] neg_hi:[0,1]
	v_pk_add_f32 v[196:197], v[196:197], v[218:219] op_sel_hi:[1,0] neg_lo:[0,1] neg_hi:[0,1]
	v_pk_mul_f32 v[194:195], v[194:195], v[218:219] op_sel:[0,1] op_sel_hi:[1,1]
	v_pk_mul_f32 v[196:197], v[196:197], v[218:219] op_sel:[0,1] op_sel_hi:[1,1]
	v_pk_fma_f32 v[194:195], v[232:233], v[194:195], v[236:237]
	v_pk_fma_f32 v[196:197], v[234:235], v[196:197], v[238:239]
	v_pk_fma_f32 v[104:105], v[194:195], s[82:83], v[104:105] op_sel_hi:[1,0,1]
	v_pk_fma_f32 v[106:107], v[196:197], s[82:83], v[106:107] op_sel_hi:[1,0,1]
	s_nop 0
	global_store_dwordx4 v129, v[104:107], s[60:61] sc1
	global_load_dwordx4 v[194:197], v129, s[60:61] offset:512
	s_waitcnt vmcnt(15)
	v_pk_add_f32 v[200:201], v[200:201], v[220:221] op_sel_hi:[1,0] neg_lo:[0,1] neg_hi:[0,1]
	v_pk_add_f32 v[202:203], v[202:203], v[220:221] op_sel_hi:[1,0] neg_lo:[0,1] neg_hi:[0,1]
	v_pk_mul_f32 v[200:201], v[200:201], v[220:221] op_sel:[0,1] op_sel_hi:[1,1]
	v_pk_mul_f32 v[202:203], v[202:203], v[220:221] op_sel:[0,1] op_sel_hi:[1,1]
	v_pk_fma_f32 v[200:201], v[232:233], v[200:201], v[236:237]
	v_pk_fma_f32 v[202:203], v[234:235], v[202:203], v[238:239]
	v_pk_fma_f32 v[100:101], v[200:201], s[82:83], v[100:101] op_sel_hi:[1,0,1]
	v_pk_fma_f32 v[102:103], v[202:203], s[82:83], v[102:103] op_sel_hi:[1,0,1]
	s_nop 0
	global_store_dwordx4 v130, v[100:103], s[60:61] sc1
	global_load_dwordx4 v[200:203], v130, s[60:61] offset:512
	s_waitcnt vmcnt(16)
	v_pk_add_f32 v[204:205], v[204:205], v[230:231] op_sel_hi:[1,0] neg_lo:[0,1] neg_hi:[0,1]
	v_pk_add_f32 v[206:207], v[206:207], v[230:231] op_sel_hi:[1,0] neg_lo:[0,1] neg_hi:[0,1]
	v_pk_mul_f32 v[204:205], v[204:205], v[230:231] op_sel:[0,1] op_sel_hi:[1,1]
	v_pk_mul_f32 v[206:207], v[206:207], v[230:231] op_sel:[0,1] op_sel_hi:[1,1]
	v_pk_fma_f32 v[204:205], v[232:233], v[204:205], v[236:237]
	v_pk_fma_f32 v[206:207], v[234:235], v[206:207], v[238:239]
	v_pk_fma_f32 v[92:93], v[204:205], s[82:83], v[92:93] op_sel_hi:[1,0,1]
	v_pk_fma_f32 v[94:95], v[206:207], s[82:83], v[94:95] op_sel_hi:[1,0,1]
	s_nop 0
	global_store_dwordx4 v131, v[92:95], s[60:61] sc1
	global_load_dwordx4 v[204:207], v131, s[60:61] offset:512
	global_load_dwordx4 v[232:235], v249, s[44:45] offset:64
	global_load_dwordx4 v[236:239], v249, s[46:47] offset:64
	s_waitcnt vmcnt(16)
	v_pk_add_f32 v[174:175], v[174:175], v[208:209] op_sel_hi:[1,0] neg_lo:[0,1] neg_hi:[0,1]
	v_pk_add_f32 v[176:177], v[176:177], v[208:209] op_sel_hi:[1,0] neg_lo:[0,1] neg_hi:[0,1]
	v_pk_mul_f32 v[174:175], v[174:175], v[208:209] op_sel:[0,1] op_sel_hi:[1,1]
	v_pk_mul_f32 v[176:177], v[176:177], v[208:209] op_sel:[0,1] op_sel_hi:[1,1]
	v_pk_fma_f32 v[174:175], v[240:241], v[174:175], v[244:245]
	v_pk_fma_f32 v[176:177], v[242:243], v[176:177], v[246:247]
	v_pk_fma_f32 v[64:65], v[174:175], s[82:83], v[64:65] op_sel_hi:[1,0,1]
	v_pk_fma_f32 v[66:67], v[176:177], s[82:83], v[66:67] op_sel_hi:[1,0,1]
	s_nop 0
	global_store_dwordx4 v124, v[64:67], s[60:61] offset:512 sc1
	global_load_dwordx4 v[174:177], v124, s[60:61] offset:64
	s_waitcnt vmcnt(16)
	v_pk_add_f32 v[178:179], v[178:179], v[210:211] op_sel_hi:[1,0] neg_lo:[0,1] neg_hi:[0,1]
	v_pk_add_f32 v[180:181], v[180:181], v[210:211] op_sel_hi:[1,0] neg_lo:[0,1] neg_hi:[0,1]
	v_pk_mul_f32 v[178:179], v[178:179], v[210:211] op_sel:[0,1] op_sel_hi:[1,1]
	v_pk_mul_f32 v[180:181], v[180:181], v[210:211] op_sel:[0,1] op_sel_hi:[1,1]
	v_pk_fma_f32 v[178:179], v[240:241], v[178:179], v[244:245]
	v_pk_fma_f32 v[180:181], v[242:243], v[180:181], v[246:247]
	v_pk_fma_f32 v[56:57], v[178:179], s[82:83], v[56:57] op_sel_hi:[1,0,1]
	v_pk_fma_f32 v[58:59], v[180:181], s[82:83], v[58:59] op_sel_hi:[1,0,1]
	s_nop 0
	global_store_dwordx4 v125, v[56:59], s[60:61] offset:512 sc1
	global_load_dwordx4 v[178:181], v125, s[60:61] offset:64
	s_waitcnt vmcnt(16)
	v_pk_add_f32 v[182:183], v[182:183], v[212:213] op_sel_hi:[1,0] neg_lo:[0,1] neg_hi:[0,1]
	v_pk_add_f32 v[184:185], v[184:185], v[212:213] op_sel_hi:[1,0] neg_lo:[0,1] neg_hi:[0,1]
	v_pk_mul_f32 v[182:183], v[182:183], v[212:213] op_sel:[0,1] op_sel_hi:[1,1]
	v_pk_mul_f32 v[184:185], v[184:185], v[212:213] op_sel:[0,1] op_sel_hi:[1,1]
	v_pk_fma_f32 v[182:183], v[240:241], v[182:183], v[244:245]
	v_pk_fma_f32 v[184:185], v[242:243], v[184:185], v[246:247]
	v_pk_fma_f32 v[52:53], v[182:183], s[82:83], v[52:53] op_sel_hi:[1,0,1]
	v_pk_fma_f32 v[54:55], v[184:185], s[82:83], v[54:55] op_sel_hi:[1,0,1]
	s_nop 0
	global_store_dwordx4 v126, v[52:55], s[60:61] offset:512 sc1
	global_load_dwordx4 v[182:185], v126, s[60:61] offset:64
	s_waitcnt vmcnt(16)
	v_pk_add_f32 v[186:187], v[186:187], v[214:215] op_sel_hi:[1,0] neg_lo:[0,1] neg_hi:[0,1]
	v_pk_add_f32 v[188:189], v[188:189], v[214:215] op_sel_hi:[1,0] neg_lo:[0,1] neg_hi:[0,1]
	v_pk_mul_f32 v[186:187], v[186:187], v[214:215] op_sel:[0,1] op_sel_hi:[1,1]
	v_pk_mul_f32 v[188:189], v[188:189], v[214:215] op_sel:[0,1] op_sel_hi:[1,1]
	v_pk_fma_f32 v[186:187], v[240:241], v[186:187], v[244:245]
	v_pk_fma_f32 v[188:189], v[242:243], v[188:189], v[246:247]
	v_pk_fma_f32 v[48:49], v[186:187], s[82:83], v[48:49] op_sel_hi:[1,0,1]
	v_pk_fma_f32 v[50:51], v[188:189], s[82:83], v[50:51] op_sel_hi:[1,0,1]
	s_nop 0
	global_store_dwordx4 v127, v[48:51], s[60:61] offset:512 sc1
	global_load_dwordx4 v[186:189], v127, s[60:61] offset:64
	s_waitcnt vmcnt(16)
	v_pk_add_f32 v[190:191], v[190:191], v[216:217] op_sel_hi:[1,0] neg_lo:[0,1] neg_hi:[0,1]
	v_pk_add_f32 v[192:193], v[192:193], v[216:217] op_sel_hi:[1,0] neg_lo:[0,1] neg_hi:[0,1]
	v_pk_mul_f32 v[190:191], v[190:191], v[216:217] op_sel:[0,1] op_sel_hi:[1,1]
	v_pk_mul_f32 v[192:193], v[192:193], v[216:217] op_sel:[0,1] op_sel_hi:[1,1]
	v_pk_fma_f32 v[190:191], v[240:241], v[190:191], v[244:245]
	v_pk_fma_f32 v[192:193], v[242:243], v[192:193], v[246:247]
	v_pk_fma_f32 v[44:45], v[190:191], s[82:83], v[44:45] op_sel_hi:[1,0,1]
	v_pk_fma_f32 v[46:47], v[192:193], s[82:83], v[46:47] op_sel_hi:[1,0,1]
	s_nop 0
	global_store_dwordx4 v128, v[44:47], s[60:61] offset:512 sc1
	global_load_dwordx4 v[190:193], v128, s[60:61] offset:64
	s_waitcnt vmcnt(16)
	v_pk_add_f32 v[194:195], v[194:195], v[218:219] op_sel_hi:[1,0] neg_lo:[0,1] neg_hi:[0,1]
	v_pk_add_f32 v[196:197], v[196:197], v[218:219] op_sel_hi:[1,0] neg_lo:[0,1] neg_hi:[0,1]
	v_pk_mul_f32 v[194:195], v[194:195], v[218:219] op_sel:[0,1] op_sel_hi:[1,1]
	v_pk_mul_f32 v[196:197], v[196:197], v[218:219] op_sel:[0,1] op_sel_hi:[1,1]
	v_pk_fma_f32 v[194:195], v[240:241], v[194:195], v[244:245]
	v_pk_fma_f32 v[196:197], v[242:243], v[196:197], v[246:247]
	v_pk_fma_f32 v[40:41], v[194:195], s[82:83], v[40:41] op_sel_hi:[1,0,1]
	v_pk_fma_f32 v[42:43], v[196:197], s[82:83], v[42:43] op_sel_hi:[1,0,1]
	s_nop 0
	global_store_dwordx4 v129, v[40:43], s[60:61] offset:512 sc1
	global_load_dwordx4 v[194:197], v129, s[60:61] offset:64
	s_waitcnt vmcnt(16)
	v_pk_add_f32 v[200:201], v[200:201], v[220:221] op_sel_hi:[1,0] neg_lo:[0,1] neg_hi:[0,1]
	v_pk_add_f32 v[202:203], v[202:203], v[220:221] op_sel_hi:[1,0] neg_lo:[0,1] neg_hi:[0,1]
	v_pk_mul_f32 v[200:201], v[200:201], v[220:221] op_sel:[0,1] op_sel_hi:[1,1]
	v_pk_mul_f32 v[202:203], v[202:203], v[220:221] op_sel:[0,1] op_sel_hi:[1,1]
	v_pk_fma_f32 v[200:201], v[240:241], v[200:201], v[244:245]
	v_pk_fma_f32 v[202:203], v[242:243], v[202:203], v[246:247]
	v_pk_fma_f32 v[36:37], v[200:201], s[82:83], v[36:37] op_sel_hi:[1,0,1]
	v_pk_fma_f32 v[38:39], v[202:203], s[82:83], v[38:39] op_sel_hi:[1,0,1]
	s_nop 0
	global_store_dwordx4 v130, v[36:39], s[60:61] offset:512 sc1
	global_load_dwordx4 v[200:203], v130, s[60:61] offset:64
	s_waitcnt vmcnt(16)
	v_pk_add_f32 v[204:205], v[204:205], v[230:231] op_sel_hi:[1,0] neg_lo:[0,1] neg_hi:[0,1]
	v_pk_add_f32 v[206:207], v[206:207], v[230:231] op_sel_hi:[1,0] neg_lo:[0,1] neg_hi:[0,1]
	v_pk_mul_f32 v[204:205], v[204:205], v[230:231] op_sel:[0,1] op_sel_hi:[1,1]
	v_pk_mul_f32 v[206:207], v[206:207], v[230:231] op_sel:[0,1] op_sel_hi:[1,1]
	v_pk_fma_f32 v[204:205], v[240:241], v[204:205], v[244:245]
	v_pk_fma_f32 v[206:207], v[242:243], v[206:207], v[246:247]
	v_pk_fma_f32 v[28:29], v[204:205], s[82:83], v[28:29] op_sel_hi:[1,0,1]
	v_pk_fma_f32 v[30:31], v[206:207], s[82:83], v[30:31] op_sel_hi:[1,0,1]
	s_nop 0
	global_store_dwordx4 v131, v[28:31], s[60:61] offset:512 sc1
	global_load_dwordx4 v[204:207], v131, s[60:61] offset:64
	global_load_dwordx4 v[240:243], v249, s[44:45] offset:576
	global_load_dwordx4 v[244:247], v249, s[46:47] offset:576
	s_waitcnt vmcnt(16)
	v_pk_add_f32 v[174:175], v[174:175], v[208:209] op_sel_hi:[1,0] neg_lo:[0,1] neg_hi:[0,1]
	v_pk_add_f32 v[176:177], v[176:177], v[208:209] op_sel_hi:[1,0] neg_lo:[0,1] neg_hi:[0,1]
	v_pk_mul_f32 v[174:175], v[174:175], v[208:209] op_sel:[0,1] op_sel_hi:[1,1]
	v_pk_mul_f32 v[176:177], v[176:177], v[208:209] op_sel:[0,1] op_sel_hi:[1,1]
	v_pk_fma_f32 v[174:175], v[232:233], v[174:175], v[236:237]
	v_pk_fma_f32 v[176:177], v[234:235], v[176:177], v[238:239]
	v_pk_fma_f32 v[96:97], v[174:175], s[82:83], v[96:97] op_sel_hi:[1,0,1]
	v_pk_fma_f32 v[98:99], v[176:177], s[82:83], v[98:99] op_sel_hi:[1,0,1]
	s_nop 0
	global_store_dwordx4 v124, v[96:99], s[60:61] offset:64 sc1
	global_load_dwordx4 v[174:177], v124, s[60:61] offset:576
	s_waitcnt vmcnt(16)
	v_pk_add_f32 v[178:179], v[178:179], v[210:211] op_sel_hi:[1,0] neg_lo:[0,1] neg_hi:[0,1]
	v_pk_add_f32 v[180:181], v[180:181], v[210:211] op_sel_hi:[1,0] neg_lo:[0,1] neg_hi:[0,1]
	v_pk_mul_f32 v[178:179], v[178:179], v[210:211] op_sel:[0,1] op_sel_hi:[1,1]
	v_pk_mul_f32 v[180:181], v[180:181], v[210:211] op_sel:[0,1] op_sel_hi:[1,1]
	v_pk_fma_f32 v[178:179], v[232:233], v[178:179], v[236:237]
	v_pk_fma_f32 v[180:181], v[234:235], v[180:181], v[238:239]
	v_pk_fma_f32 v[88:89], v[178:179], s[82:83], v[88:89] op_sel_hi:[1,0,1]
	v_pk_fma_f32 v[90:91], v[180:181], s[82:83], v[90:91] op_sel_hi:[1,0,1]
	s_nop 0
	global_store_dwordx4 v125, v[88:91], s[60:61] offset:64 sc1
	global_load_dwordx4 v[178:181], v125, s[60:61] offset:576
	s_waitcnt vmcnt(16)
	v_pk_add_f32 v[182:183], v[182:183], v[212:213] op_sel_hi:[1,0] neg_lo:[0,1] neg_hi:[0,1]
	v_pk_add_f32 v[184:185], v[184:185], v[212:213] op_sel_hi:[1,0] neg_lo:[0,1] neg_hi:[0,1]
	v_pk_mul_f32 v[182:183], v[182:183], v[212:213] op_sel:[0,1] op_sel_hi:[1,1]
	v_pk_mul_f32 v[184:185], v[184:185], v[212:213] op_sel:[0,1] op_sel_hi:[1,1]
	v_pk_fma_f32 v[182:183], v[232:233], v[182:183], v[236:237]
	v_pk_fma_f32 v[184:185], v[234:235], v[184:185], v[238:239]
	v_pk_fma_f32 v[84:85], v[182:183], s[82:83], v[84:85] op_sel_hi:[1,0,1]
	v_pk_fma_f32 v[86:87], v[184:185], s[82:83], v[86:87] op_sel_hi:[1,0,1]
	s_nop 0
	global_store_dwordx4 v126, v[84:87], s[60:61] offset:64 sc1
	global_load_dwordx4 v[182:185], v126, s[60:61] offset:576
	s_waitcnt vmcnt(16)
	v_pk_add_f32 v[186:187], v[186:187], v[214:215] op_sel_hi:[1,0] neg_lo:[0,1] neg_hi:[0,1]
	v_pk_add_f32 v[188:189], v[188:189], v[214:215] op_sel_hi:[1,0] neg_lo:[0,1] neg_hi:[0,1]
	v_pk_mul_f32 v[186:187], v[186:187], v[214:215] op_sel:[0,1] op_sel_hi:[1,1]
	v_pk_mul_f32 v[188:189], v[188:189], v[214:215] op_sel:[0,1] op_sel_hi:[1,1]
	v_pk_fma_f32 v[186:187], v[232:233], v[186:187], v[236:237]
	v_pk_fma_f32 v[188:189], v[234:235], v[188:189], v[238:239]
	v_pk_fma_f32 v[80:81], v[186:187], s[82:83], v[80:81] op_sel_hi:[1,0,1]
	v_pk_fma_f32 v[82:83], v[188:189], s[82:83], v[82:83] op_sel_hi:[1,0,1]
	s_nop 0
	global_store_dwordx4 v127, v[80:83], s[60:61] offset:64 sc1
	global_load_dwordx4 v[186:189], v127, s[60:61] offset:576
	s_waitcnt vmcnt(16)
	v_pk_add_f32 v[190:191], v[190:191], v[216:217] op_sel_hi:[1,0] neg_lo:[0,1] neg_hi:[0,1]
	v_pk_add_f32 v[192:193], v[192:193], v[216:217] op_sel_hi:[1,0] neg_lo:[0,1] neg_hi:[0,1]
	v_pk_mul_f32 v[190:191], v[190:191], v[216:217] op_sel:[0,1] op_sel_hi:[1,1]
	v_pk_mul_f32 v[192:193], v[192:193], v[216:217] op_sel:[0,1] op_sel_hi:[1,1]
	v_pk_fma_f32 v[190:191], v[232:233], v[190:191], v[236:237]
	v_pk_fma_f32 v[192:193], v[234:235], v[192:193], v[238:239]
	v_pk_fma_f32 v[76:77], v[190:191], s[82:83], v[76:77] op_sel_hi:[1,0,1]
	v_pk_fma_f32 v[78:79], v[192:193], s[82:83], v[78:79] op_sel_hi:[1,0,1]
	s_nop 0
	global_store_dwordx4 v128, v[76:79], s[60:61] offset:64 sc1
	global_load_dwordx4 v[190:193], v128, s[60:61] offset:576
	s_waitcnt vmcnt(16)
	v_pk_add_f32 v[194:195], v[194:195], v[218:219] op_sel_hi:[1,0] neg_lo:[0,1] neg_hi:[0,1]
	v_pk_add_f32 v[196:197], v[196:197], v[218:219] op_sel_hi:[1,0] neg_lo:[0,1] neg_hi:[0,1]
	v_pk_mul_f32 v[194:195], v[194:195], v[218:219] op_sel:[0,1] op_sel_hi:[1,1]
	v_pk_mul_f32 v[196:197], v[196:197], v[218:219] op_sel:[0,1] op_sel_hi:[1,1]
	v_pk_fma_f32 v[194:195], v[232:233], v[194:195], v[236:237]
	v_pk_fma_f32 v[196:197], v[234:235], v[196:197], v[238:239]
	v_pk_fma_f32 v[72:73], v[194:195], s[82:83], v[72:73] op_sel_hi:[1,0,1]
	v_pk_fma_f32 v[74:75], v[196:197], s[82:83], v[74:75] op_sel_hi:[1,0,1]
	s_nop 0
	global_store_dwordx4 v129, v[72:75], s[60:61] offset:64 sc1
	global_load_dwordx4 v[194:197], v129, s[60:61] offset:576
	s_waitcnt vmcnt(16)
	v_pk_add_f32 v[200:201], v[200:201], v[220:221] op_sel_hi:[1,0] neg_lo:[0,1] neg_hi:[0,1]
	v_pk_add_f32 v[202:203], v[202:203], v[220:221] op_sel_hi:[1,0] neg_lo:[0,1] neg_hi:[0,1]
	v_pk_mul_f32 v[200:201], v[200:201], v[220:221] op_sel:[0,1] op_sel_hi:[1,1]
	v_pk_mul_f32 v[202:203], v[202:203], v[220:221] op_sel:[0,1] op_sel_hi:[1,1]
	v_pk_fma_f32 v[200:201], v[232:233], v[200:201], v[236:237]
	v_pk_fma_f32 v[202:203], v[234:235], v[202:203], v[238:239]
	v_pk_fma_f32 v[68:69], v[200:201], s[82:83], v[68:69] op_sel_hi:[1,0,1]
	v_pk_fma_f32 v[70:71], v[202:203], s[82:83], v[70:71] op_sel_hi:[1,0,1]
	s_nop 0
	global_store_dwordx4 v130, v[68:71], s[60:61] offset:64 sc1
	global_load_dwordx4 v[200:203], v130, s[60:61] offset:576
	s_waitcnt vmcnt(16)
	v_pk_add_f32 v[204:205], v[204:205], v[230:231] op_sel_hi:[1,0] neg_lo:[0,1] neg_hi:[0,1]
	v_pk_add_f32 v[206:207], v[206:207], v[230:231] op_sel_hi:[1,0] neg_lo:[0,1] neg_hi:[0,1]
	v_pk_mul_f32 v[204:205], v[204:205], v[230:231] op_sel:[0,1] op_sel_hi:[1,1]
	v_pk_mul_f32 v[206:207], v[206:207], v[230:231] op_sel:[0,1] op_sel_hi:[1,1]
	v_pk_fma_f32 v[204:205], v[232:233], v[204:205], v[236:237]
	v_pk_fma_f32 v[206:207], v[234:235], v[206:207], v[238:239]
	v_pk_fma_f32 v[60:61], v[204:205], s[82:83], v[60:61] op_sel_hi:[1,0,1]
	v_pk_fma_f32 v[62:63], v[206:207], s[82:83], v[62:63] op_sel_hi:[1,0,1]
	s_nop 0
	global_store_dwordx4 v131, v[60:63], s[60:61] offset:64 sc1
	global_load_dwordx4 v[204:207], v131, s[60:61] offset:576
	s_waitcnt vmcnt(14)
	v_pk_add_f32 v[174:175], v[174:175], v[208:209] op_sel_hi:[1,0] neg_lo:[0,1] neg_hi:[0,1]
	v_pk_add_f32 v[176:177], v[176:177], v[208:209] op_sel_hi:[1,0] neg_lo:[0,1] neg_hi:[0,1]
	v_pk_mul_f32 v[174:175], v[174:175], v[208:209] op_sel:[0,1] op_sel_hi:[1,1]
	v_pk_mul_f32 v[176:177], v[176:177], v[208:209] op_sel:[0,1] op_sel_hi:[1,1]
	v_pk_fma_f32 v[174:175], v[240:241], v[174:175], v[244:245]
	v_pk_fma_f32 v[176:177], v[242:243], v[176:177], v[246:247]
	v_pk_fma_f32 v[32:33], v[174:175], s[82:83], v[32:33] op_sel_hi:[1,0,1]
	v_pk_fma_f32 v[34:35], v[176:177], s[82:83], v[34:35] op_sel_hi:[1,0,1]
	s_nop 0
	global_store_dwordx4 v124, v[32:35], s[60:61] offset:576 sc1
	s_waitcnt vmcnt(13)
	v_pk_add_f32 v[178:179], v[178:179], v[210:211] op_sel_hi:[1,0] neg_lo:[0,1] neg_hi:[0,1]
	v_pk_add_f32 v[180:181], v[180:181], v[210:211] op_sel_hi:[1,0] neg_lo:[0,1] neg_hi:[0,1]
	v_pk_mul_f32 v[178:179], v[178:179], v[210:211] op_sel:[0,1] op_sel_hi:[1,1]
	v_pk_mul_f32 v[180:181], v[180:181], v[210:211] op_sel:[0,1] op_sel_hi:[1,1]
	v_pk_fma_f32 v[178:179], v[240:241], v[178:179], v[244:245]
	v_pk_fma_f32 v[180:181], v[242:243], v[180:181], v[246:247]
	v_pk_fma_f32 v[24:25], v[178:179], s[82:83], v[24:25] op_sel_hi:[1,0,1]
	v_pk_fma_f32 v[26:27], v[180:181], s[82:83], v[26:27] op_sel_hi:[1,0,1]
	s_nop 0
	global_store_dwordx4 v125, v[24:27], s[60:61] offset:576 sc1
	s_waitcnt vmcnt(12)
	v_pk_add_f32 v[182:183], v[182:183], v[212:213] op_sel_hi:[1,0] neg_lo:[0,1] neg_hi:[0,1]
	v_pk_add_f32 v[184:185], v[184:185], v[212:213] op_sel_hi:[1,0] neg_lo:[0,1] neg_hi:[0,1]
	v_pk_mul_f32 v[182:183], v[182:183], v[212:213] op_sel:[0,1] op_sel_hi:[1,1]
	v_pk_mul_f32 v[184:185], v[184:185], v[212:213] op_sel:[0,1] op_sel_hi:[1,1]
	v_pk_fma_f32 v[182:183], v[240:241], v[182:183], v[244:245]
	v_pk_fma_f32 v[184:185], v[242:243], v[184:185], v[246:247]
	v_pk_fma_f32 v[20:21], v[182:183], s[82:83], v[20:21] op_sel_hi:[1,0,1]
	v_pk_fma_f32 v[22:23], v[184:185], s[82:83], v[22:23] op_sel_hi:[1,0,1]
	s_nop 0
	global_store_dwordx4 v126, v[20:23], s[60:61] offset:576 sc1
	s_waitcnt vmcnt(11)
	v_pk_add_f32 v[186:187], v[186:187], v[214:215] op_sel_hi:[1,0] neg_lo:[0,1] neg_hi:[0,1]
	v_pk_add_f32 v[188:189], v[188:189], v[214:215] op_sel_hi:[1,0] neg_lo:[0,1] neg_hi:[0,1]
	v_pk_mul_f32 v[186:187], v[186:187], v[214:215] op_sel:[0,1] op_sel_hi:[1,1]
	v_pk_mul_f32 v[188:189], v[188:189], v[214:215] op_sel:[0,1] op_sel_hi:[1,1]
	v_pk_fma_f32 v[186:187], v[240:241], v[186:187], v[244:245]
	v_pk_fma_f32 v[188:189], v[242:243], v[188:189], v[246:247]
	v_pk_fma_f32 v[16:17], v[186:187], s[82:83], v[16:17] op_sel_hi:[1,0,1]
	v_pk_fma_f32 v[18:19], v[188:189], s[82:83], v[18:19] op_sel_hi:[1,0,1]
	s_nop 0
	global_store_dwordx4 v127, v[16:19], s[60:61] offset:576 sc1
	s_waitcnt vmcnt(10)
	v_pk_add_f32 v[190:191], v[190:191], v[216:217] op_sel_hi:[1,0] neg_lo:[0,1] neg_hi:[0,1]
	v_pk_add_f32 v[192:193], v[192:193], v[216:217] op_sel_hi:[1,0] neg_lo:[0,1] neg_hi:[0,1]
	v_pk_mul_f32 v[190:191], v[190:191], v[216:217] op_sel:[0,1] op_sel_hi:[1,1]
	v_pk_mul_f32 v[192:193], v[192:193], v[216:217] op_sel:[0,1] op_sel_hi:[1,1]
	v_pk_fma_f32 v[190:191], v[240:241], v[190:191], v[244:245]
	v_pk_fma_f32 v[192:193], v[242:243], v[192:193], v[246:247]
	v_pk_fma_f32 v[12:13], v[190:191], s[82:83], v[12:13] op_sel_hi:[1,0,1]
	v_pk_fma_f32 v[14:15], v[192:193], s[82:83], v[14:15] op_sel_hi:[1,0,1]
	s_nop 0
	global_store_dwordx4 v128, v[12:15], s[60:61] offset:576 sc1
	s_waitcnt vmcnt(9)
	v_pk_add_f32 v[194:195], v[194:195], v[218:219] op_sel_hi:[1,0] neg_lo:[0,1] neg_hi:[0,1]
	v_pk_add_f32 v[196:197], v[196:197], v[218:219] op_sel_hi:[1,0] neg_lo:[0,1] neg_hi:[0,1]
	v_pk_mul_f32 v[194:195], v[194:195], v[218:219] op_sel:[0,1] op_sel_hi:[1,1]
	v_pk_mul_f32 v[196:197], v[196:197], v[218:219] op_sel:[0,1] op_sel_hi:[1,1]
	v_pk_fma_f32 v[194:195], v[240:241], v[194:195], v[244:245]
	v_pk_fma_f32 v[196:197], v[242:243], v[196:197], v[246:247]
	v_pk_fma_f32 v[8:9], v[194:195], s[82:83], v[8:9] op_sel_hi:[1,0,1]
	v_pk_fma_f32 v[10:11], v[196:197], s[82:83], v[10:11] op_sel_hi:[1,0,1]
	s_nop 0
	global_store_dwordx4 v129, v[8:11], s[60:61] offset:576 sc1
	s_waitcnt vmcnt(8)
	v_pk_add_f32 v[200:201], v[200:201], v[220:221] op_sel_hi:[1,0] neg_lo:[0,1] neg_hi:[0,1]
	v_pk_add_f32 v[202:203], v[202:203], v[220:221] op_sel_hi:[1,0] neg_lo:[0,1] neg_hi:[0,1]
	v_pk_mul_f32 v[200:201], v[200:201], v[220:221] op_sel:[0,1] op_sel_hi:[1,1]
	v_pk_mul_f32 v[202:203], v[202:203], v[220:221] op_sel:[0,1] op_sel_hi:[1,1]
	v_pk_fma_f32 v[200:201], v[240:241], v[200:201], v[244:245]
	v_pk_fma_f32 v[202:203], v[242:243], v[202:203], v[246:247]
	v_pk_fma_f32 v[4:5], v[200:201], s[82:83], v[4:5] op_sel_hi:[1,0,1]
	v_pk_fma_f32 v[6:7], v[202:203], s[82:83], v[6:7] op_sel_hi:[1,0,1]
	s_nop 0
	global_store_dwordx4 v130, v[4:7], s[60:61] offset:576 sc1
	s_waitcnt vmcnt(7)
	v_pk_add_f32 v[204:205], v[204:205], v[230:231] op_sel_hi:[1,0] neg_lo:[0,1] neg_hi:[0,1]
	v_pk_add_f32 v[206:207], v[206:207], v[230:231] op_sel_hi:[1,0] neg_lo:[0,1] neg_hi:[0,1]
	v_pk_mul_f32 v[204:205], v[204:205], v[230:231] op_sel:[0,1] op_sel_hi:[1,1]
	v_pk_mul_f32 v[206:207], v[206:207], v[230:231] op_sel:[0,1] op_sel_hi:[1,1]
	v_pk_fma_f32 v[204:205], v[240:241], v[204:205], v[244:245]
	v_pk_fma_f32 v[206:207], v[242:243], v[206:207], v[246:247]
	v_pk_fma_f32 v[0:1], v[204:205], s[82:83], v[0:1] op_sel_hi:[1,0,1]
	v_pk_fma_f32 v[2:3], v[206:207], s[82:83], v[2:3] op_sel_hi:[1,0,1]
	s_nop 0
	global_store_dwordx4 v131, v[0:3], s[60:61] offset:576 sc1
	s_nop 3
	s_mov_b64 s[60:61], -1
	s_andn2_b64 vcc, exec, s[36:37]
	s_cbranch_vccnz .LBB0_1075
	s_andn2_b64 vcc, exec, s[48:49]
	s_cbranch_vccnz .LBB0_1074
	s_barrier
	s_branch .LBB0_1074
